# GEMM K-loops: removed the redundant s_setprio 0 / s_setprio 1 pair between the two MMA groups of each phase (2 fewer issue slots between MFMAs)
# baseline (speedup 1.0000x reference)
; #define PG8_STAGE(bufoff, gbase, voff) do { _Pragma("unroll") for (int _i = 0; _i < 2; ++_i) \
;         __builtin_amdgcn_global_load_lds((const unsigned*)((const char*)(gbase) + (voff)[_i]), (LAS unsigned*)(lds + (bufoff) + ldsw + _i * 8192), 16, 0, 0); } while (0)
; #define PG8_LDA(dst, b, h) do { _Pragma("unroll") for (int m = 0; m < 4; ++m) _Pragma("unroll") for (int k = 0; k < 2; ++k) dst[m][k] = *(const LAS bf16x8*)(lds + PG8_SA(b, h) + aoff + m * 2048 + k * 1024); } while (0)
; #define PG8_LDB(dst, b, h) do { _Pragma("unroll") for (int n = 0; n < 2; ++n) _Pragma("unroll") for (int k = 0; k < 2; ++k) dst[n][k] = *(const LAS bf16x8*)(lds + PG8_SB(b, h) + boff + n * 2048 + k * 1024); } while (0)
; #define PG8_MMA(ai, bj, At, Bt) do { __builtin_amdgcn_s_setprio(1); _Pragma("unroll") for (int m = 0; m < 4; ++m) _Pragma("unroll") for (int n = 0; n < 2; ++n) _Pragma("unroll") for (int k = 0; k < 2; ++k) \
;         acc[ai][bj][m][n] = __builtin_amdgcn_mfma_f32_16x16x32_bf16(Bt[n][k], At[m][k], acc[ai][bj][m][n], 0, 0, 0); __builtin_amdgcn_s_setprio(0); } while (0)
; #define PG8_WAIT_V(n) asm volatile("s_waitcnt vmcnt(" #n ")" ::: "memory")
; #define PG8_WAIT_L(n) asm volatile("s_waitcnt lgkmcnt(" #n ")" ::: "memory")
; #define PG8_BAR __builtin_amdgcn_s_barrier()
; #define PG8_SCHED __builtin_amdgcn_sched_barrier(0)
; template <class Epi>
; __device__ __forceinline__ void gemm_phase(LAS unsigned char* lds, const Gemm g, const StaticOrder& S, const Epi& E) {
;     ...
;             PG8_LDB(B0, 0, 0); PG8_LDB(B1, 0, 1); PG8_SCHED; PG8_LDA(At, 0, 0); PG8_STAGE(PG8_SA(1, 1), a1 + hstepA, voffA);
;             PG8_WAIT_V(8); PG8_WAIT_L(0); PG8_BAR; PG8_MMA(0, 0, At, B0); PG8_MMA(0, 1, At, B1); PG8_BAR; PG8_SCHED;
;             PG8_LDA(At, 0, 1); PG8_STAGE(PG8_SB(0, 0), b2, voffB); PG8_STAGE(PG8_SB(0, 1), b2 + hstepB, voffB); PG8_STAGE(PG8_SA(0, 0), a2, voffA);
;             PG8_WAIT_V(8); PG8_WAIT_L(0); PG8_BAR; PG8_MMA(1, 0, At, B0); PG8_MMA(1, 1, At, B1); PG8_BAR; PG8_SCHED;
.LBB0_187:
	s_add_i32 s16, s15, 2
	s_add_u32 s17, s0, 0xfff70080
	s_addc_u32 s18, s1, -1
	s_add_i32 s20, 0, 0x10000
	s_cmp_eq_u32 s81, s15
	s_cselect_b32 s41, s91, s18
	s_cselect_b32 s40, s90, s17
	v_add_u32_e32 v0, s20, v157
	s_cselect_b32 s19, s93, s14
	s_cselect_b32 s18, s92, s13
	s_add_i32 s15, 0, 0x14000
	ds_read_b128 v[142:145], v0
	ds_read_b128 v[146:149], v0 offset:1024
	ds_read_b128 v[150:153], v0 offset:2048
	ds_read_b128 v[160:163], v0 offset:3072
	v_add_u32_e32 v0, s15, v157
	ds_read_b128 v[164:167], v0
	ds_read_b128 v[168:171], v0 offset:1024
	ds_read_b128 v[172:175], v0 offset:2048
	ds_read_b128 v[176:179], v0 offset:3072
	v_lshl_add_u64 v[214:215], s[0:1], 0, v[140:141]
	s_add_i32 m0, s53, 0xc000
	ds_read_b128 v[182:185], v159
	ds_read_b128 v[186:189], v159 offset:1024
	ds_read_b128 v[190:193], v159 offset:2048
	ds_read_b128 v[194:197], v159 offset:3072
	ds_read_b128 v[198:201], v159 offset:4096
	ds_read_b128 v[202:205], v159 offset:5120
	ds_read_b128 v[206:209], v159 offset:6144
	ds_read_b128 v[210:213], v159 offset:7168
	global_load_lds_dwordx4 v[214:215], off
	v_lshl_add_u64 v[214:215], s[0:1], 0, v[138:139]
	s_add_i32 m0, s53, 0xe000
	s_nop 0
	global_load_lds_dwordx4 v[214:215], off
	s_waitcnt vmcnt(8)
	s_waitcnt lgkmcnt(0)
	s_barrier
	s_setprio 1
	s_waitcnt lgkmcnt(0)
	v_mfma_f32_16x16x32_bf16 v[126:129], v[142:145], v[182:185], v[126:129]
	v_mfma_f32_16x16x32_bf16 v[122:125], v[150:153], v[182:185], v[122:125]
	v_mfma_f32_16x16x32_bf16 v[110:113], v[142:145], v[190:193], v[110:113]
	v_mfma_f32_16x16x32_bf16 v[106:109], v[150:153], v[190:193], v[106:109]
	v_mfma_f32_16x16x32_bf16 v[94:97], v[142:145], v[198:201], v[94:97]
	v_mfma_f32_16x16x32_bf16 v[90:93], v[150:153], v[198:201], v[90:93]
	v_mfma_f32_16x16x32_bf16 v[78:81], v[142:145], v[206:209], v[78:81]
	v_mfma_f32_16x16x32_bf16 v[74:77], v[150:153], v[206:209], v[74:77]
	v_mfma_f32_16x16x32_bf16 v[126:129], v[146:149], v[186:189], v[126:129]
	v_mfma_f32_16x16x32_bf16 v[122:125], v[160:163], v[186:189], v[122:125]
	v_mfma_f32_16x16x32_bf16 v[110:113], v[146:149], v[194:197], v[110:113]
	v_mfma_f32_16x16x32_bf16 v[106:109], v[160:163], v[194:197], v[106:109]
	v_mfma_f32_16x16x32_bf16 v[94:97], v[146:149], v[202:205], v[94:97]
	v_mfma_f32_16x16x32_bf16 v[90:93], v[160:163], v[202:205], v[90:93]
	v_mfma_f32_16x16x32_bf16 v[78:81], v[146:149], v[210:213], v[78:81]
	v_mfma_f32_16x16x32_bf16 v[74:77], v[160:163], v[210:213], v[74:77]
	v_mfma_f32_16x16x32_bf16 v[118:121], v[164:167], v[182:185], v[118:121]
	v_mfma_f32_16x16x32_bf16 v[114:117], v[172:175], v[182:185], v[114:117]
	v_mfma_f32_16x16x32_bf16 v[102:105], v[164:167], v[190:193], v[102:105]
	v_mfma_f32_16x16x32_bf16 v[98:101], v[172:175], v[190:193], v[98:101]
	v_mfma_f32_16x16x32_bf16 v[86:89], v[164:167], v[198:201], v[86:89]
	v_mfma_f32_16x16x32_bf16 v[82:85], v[172:175], v[198:201], v[82:85]
	v_mfma_f32_16x16x32_bf16 v[70:73], v[164:167], v[206:209], v[70:73]
	v_mfma_f32_16x16x32_bf16 v[66:69], v[172:175], v[206:209], v[66:69]
	v_mfma_f32_16x16x32_bf16 v[118:121], v[168:171], v[186:189], v[118:121]
	v_mfma_f32_16x16x32_bf16 v[114:117], v[176:179], v[186:189], v[114:117]
	v_mfma_f32_16x16x32_bf16 v[102:105], v[168:171], v[194:197], v[102:105]
	v_mfma_f32_16x16x32_bf16 v[98:101], v[176:179], v[194:197], v[98:101]
	v_mfma_f32_16x16x32_bf16 v[86:89], v[168:171], v[202:205], v[86:89]
	v_mfma_f32_16x16x32_bf16 v[82:85], v[176:179], v[202:205], v[82:85]
	v_mfma_f32_16x16x32_bf16 v[70:73], v[168:171], v[210:213], v[70:73]
	v_mfma_f32_16x16x32_bf16 v[66:69], v[176:179], v[210:213], v[66:69]
	s_setprio 0
	s_barrier
	s_add_i32 s17, s20, s52
	v_lshl_add_u64 v[214:215], s[18:19], 0, v[132:133]
	s_mov_b32 m0, s17
	ds_read_b128 v[182:185], v159 offset:16384
	ds_read_b128 v[186:189], v159 offset:17408
	ds_read_b128 v[190:193], v159 offset:18432
	ds_read_b128 v[194:197], v159 offset:19456
	ds_read_b128 v[198:201], v159 offset:20480
	ds_read_b128 v[202:205], v159 offset:21504
	ds_read_b128 v[206:209], v159 offset:22528
	ds_read_b128 v[210:213], v159 offset:23552
	global_load_lds_dwordx4 v[214:215], off
	s_add_i32 m0, s17, 0x2000
	v_lshl_add_u64 v[216:217], s[18:19], 0, v[136:137]
	s_add_u32 s18, s18, s50
	s_addc_u32 s19, s19, 0
	s_add_i32 s15, s15, s52
	global_load_lds_dwordx4 v[216:217], off
	v_lshl_add_u64 v[218:219], s[18:19], 0, v[132:133]
	s_mov_b32 m0, s15
	v_lshl_add_u64 v[220:221], s[18:19], 0, v[136:137]
	global_load_lds_dwordx4 v[218:219], off
	s_add_i32 m0, s15, 0x2000
	v_lshl_add_u64 v[222:223], s[40:41], 0, v[130:131]
	global_load_lds_dwordx4 v[220:221], off
	s_mov_b32 m0, s53
	v_lshl_add_u64 v[224:225], s[40:41], 0, v[134:135]
	global_load_lds_dwordx4 v[222:223], off
	s_mov_b32 m0, s98
	s_nop 0
	global_load_lds_dwordx4 v[224:225], off
	s_waitcnt vmcnt(8)
	s_waitcnt lgkmcnt(0)
	s_barrier
; #define PG8_STAGE(bufoff, gbase, voff) do { _Pragma("unroll") for (int _i = 0; _i < 2; ++_i) \
;         __builtin_amdgcn_global_load_lds((const unsigned*)((const char*)(gbase) + (voff)[_i]), (LAS unsigned*)(lds + (bufoff) + ldsw + _i * 8192), 16, 0, 0); } while (0)
; #define PG8_LDA(dst, b, h) do { _Pragma("unroll") for (int m = 0; m < 4; ++m) _Pragma("unroll") for (int k = 0; k < 2; ++k) dst[m][k] = *(const LAS bf16x8*)(lds + PG8_SA(b, h) + aoff + m * 2048 + k * 1024); } while (0)
; #define PG8_LDB(dst, b, h) do { _Pragma("unroll") for (int n = 0; n < 2; ++n) _Pragma("unroll") for (int k = 0; k < 2; ++k) dst[n][k] = *(const LAS bf16x8*)(lds + PG8_SB(b, h) + boff + n * 2048 + k * 1024); } while (0)
; #define PG8_MMA(ai, bj, At, Bt) do { __builtin_amdgcn_s_setprio(1); _Pragma("unroll") for (int m = 0; m < 4; ++m) _Pragma("unroll") for (int n = 0; n < 2; ++n) _Pragma("unroll") for (int k = 0; k < 2; ++k) \
;         acc[ai][bj][m][n] = __builtin_amdgcn_mfma_f32_16x16x32_bf16(Bt[n][k], At[m][k], acc[ai][bj][m][n], 0, 0, 0); __builtin_amdgcn_s_setprio(0); } while (0)
; #define PG8_WAIT_V(n) asm volatile("s_waitcnt vmcnt(" #n ")" ::: "memory")
; #define PG8_WAIT_L(n) asm volatile("s_waitcnt lgkmcnt(" #n ")" ::: "memory")
; #define PG8_BAR __builtin_amdgcn_s_barrier()
; #define PG8_SCHED __builtin_amdgcn_sched_barrier(0)
; template <class Epi>
; __device__ __forceinline__ void gemm_phase(LAS unsigned char* lds, const Gemm g, const StaticOrder& S, const Epi& E) {
;     ...
;             PG8_WAIT_V(8); PG8_WAIT_L(0); PG8_BAR; PG8_MMA(1, 0, At, B0); PG8_MMA(1, 1, At, B1); PG8_BAR; PG8_SCHED;
;             PG8_LDB(B0, 1, 0); PG8_LDB(B1, 1, 1); PG8_SCHED; PG8_LDA(At, 1, 0); PG8_STAGE(PG8_SA(0, 1), a2 + hstepA, voffA);
;             PG8_WAIT_V(8); PG8_WAIT_L(0); PG8_BAR; PG8_MMA(0, 0, At, B0); PG8_MMA(0, 1, At, B1); PG8_BAR; PG8_SCHED;
	s_setprio 1
	s_waitcnt lgkmcnt(0)
	v_mfma_f32_16x16x32_bf16 v[62:65], v[142:145], v[182:185], v[62:65]
	v_mfma_f32_16x16x32_bf16 v[58:61], v[150:153], v[182:185], v[58:61]
	v_mfma_f32_16x16x32_bf16 v[46:49], v[142:145], v[190:193], v[46:49]
	v_mfma_f32_16x16x32_bf16 v[42:45], v[150:153], v[190:193], v[42:45]
	v_mfma_f32_16x16x32_bf16 v[30:33], v[142:145], v[198:201], v[30:33]
	v_mfma_f32_16x16x32_bf16 v[26:29], v[150:153], v[198:201], v[26:29]
	v_mfma_f32_16x16x32_bf16 v[14:17], v[142:145], v[206:209], v[14:17]
	v_mfma_f32_16x16x32_bf16 v[10:13], v[150:153], v[206:209], v[10:13]
	v_mfma_f32_16x16x32_bf16 v[62:65], v[146:149], v[186:189], v[62:65]
	v_mfma_f32_16x16x32_bf16 v[58:61], v[160:163], v[186:189], v[58:61]
	v_mfma_f32_16x16x32_bf16 v[46:49], v[146:149], v[194:197], v[46:49]
	v_mfma_f32_16x16x32_bf16 v[42:45], v[160:163], v[194:197], v[42:45]
	v_mfma_f32_16x16x32_bf16 v[30:33], v[146:149], v[202:205], v[30:33]
	v_mfma_f32_16x16x32_bf16 v[26:29], v[160:163], v[202:205], v[26:29]
	v_mfma_f32_16x16x32_bf16 v[14:17], v[146:149], v[210:213], v[14:17]
	v_mfma_f32_16x16x32_bf16 v[10:13], v[160:163], v[210:213], v[10:13]
	v_mfma_f32_16x16x32_bf16 v[54:57], v[164:167], v[182:185], v[54:57]
	v_mfma_f32_16x16x32_bf16 v[50:53], v[172:175], v[182:185], v[50:53]
	v_mfma_f32_16x16x32_bf16 v[38:41], v[164:167], v[190:193], v[38:41]
	v_mfma_f32_16x16x32_bf16 v[34:37], v[172:175], v[190:193], v[34:37]
	v_mfma_f32_16x16x32_bf16 v[22:25], v[164:167], v[198:201], v[22:25]
	v_mfma_f32_16x16x32_bf16 v[18:21], v[172:175], v[198:201], v[18:21]
	v_mfma_f32_16x16x32_bf16 v[6:9], v[164:167], v[206:209], v[6:9]
	v_mfma_f32_16x16x32_bf16 v[2:5], v[172:175], v[206:209], v[2:5]
	v_mfma_f32_16x16x32_bf16 v[54:57], v[168:171], v[186:189], v[54:57]
	v_mfma_f32_16x16x32_bf16 v[50:53], v[176:179], v[186:189], v[50:53]
	v_mfma_f32_16x16x32_bf16 v[38:41], v[168:171], v[194:197], v[38:41]
	v_mfma_f32_16x16x32_bf16 v[34:37], v[176:179], v[194:197], v[34:37]
	v_mfma_f32_16x16x32_bf16 v[22:25], v[168:171], v[202:205], v[22:25]
	v_mfma_f32_16x16x32_bf16 v[18:21], v[176:179], v[202:205], v[18:21]
	v_mfma_f32_16x16x32_bf16 v[6:9], v[168:171], v[210:213], v[6:9]
	v_mfma_f32_16x16x32_bf16 v[2:5], v[176:179], v[210:213], v[2:5]
	s_setprio 0
	s_barrier
	s_add_i32 s15, 0, 0x18000
	v_add_u32_e32 v0, s15, v157
	s_add_i32 s17, 0, 0x1c000
	ds_read_b128 v[142:145], v0
	ds_read_b128 v[146:149], v0 offset:1024
	ds_read_b128 v[150:153], v0 offset:2048
	ds_read_b128 v[160:163], v0 offset:3072
	v_add_u32_e32 v0, s17, v157
	ds_read_b128 v[164:167], v0
	ds_read_b128 v[168:171], v0 offset:1024
	ds_read_b128 v[172:175], v0 offset:2048
	ds_read_b128 v[176:179], v0 offset:3072
	s_add_u32 s18, s40, 0x90000
	s_addc_u32 s19, s41, 0
	s_mov_b32 m0, s99
	v_lshl_add_u64 v[226:227], s[18:19], 0, v[130:131]
	ds_read_b128 v[182:185], v159 offset:32768
	ds_read_b128 v[186:189], v159 offset:33792
	ds_read_b128 v[190:193], v159 offset:34816
	ds_read_b128 v[194:197], v159 offset:35840
	ds_read_b128 v[198:201], v159 offset:36864
	ds_read_b128 v[202:205], v159 offset:37888
	ds_read_b128 v[206:209], v159 offset:38912
	ds_read_b128 v[210:213], v159 offset:39936
	global_load_lds_dwordx4 v[226:227], off
	v_lshl_add_u64 v[226:227], s[18:19], 0, v[134:135]
	s_mov_b32 m0, s56
	s_nop 0
	global_load_lds_dwordx4 v[226:227], off
	s_waitcnt vmcnt(8)
	s_waitcnt lgkmcnt(0)
	s_barrier
	s_setprio 1
	s_waitcnt lgkmcnt(0)
	v_mfma_f32_16x16x32_bf16 v[126:129], v[142:145], v[182:185], v[126:129]
	v_mfma_f32_16x16x32_bf16 v[122:125], v[150:153], v[182:185], v[122:125]
	v_mfma_f32_16x16x32_bf16 v[110:113], v[142:145], v[190:193], v[110:113]
	v_mfma_f32_16x16x32_bf16 v[106:109], v[150:153], v[190:193], v[106:109]
	v_mfma_f32_16x16x32_bf16 v[94:97], v[142:145], v[198:201], v[94:97]
	v_mfma_f32_16x16x32_bf16 v[90:93], v[150:153], v[198:201], v[90:93]
	v_mfma_f32_16x16x32_bf16 v[78:81], v[142:145], v[206:209], v[78:81]
	v_mfma_f32_16x16x32_bf16 v[74:77], v[150:153], v[206:209], v[74:77]
	v_mfma_f32_16x16x32_bf16 v[126:129], v[146:149], v[186:189], v[126:129]
	v_mfma_f32_16x16x32_bf16 v[122:125], v[160:163], v[186:189], v[122:125]
	v_mfma_f32_16x16x32_bf16 v[110:113], v[146:149], v[194:197], v[110:113]
	v_mfma_f32_16x16x32_bf16 v[106:109], v[160:163], v[194:197], v[106:109]
	v_mfma_f32_16x16x32_bf16 v[94:97], v[146:149], v[202:205], v[94:97]
	v_mfma_f32_16x16x32_bf16 v[90:93], v[160:163], v[202:205], v[90:93]
	v_mfma_f32_16x16x32_bf16 v[78:81], v[146:149], v[210:213], v[78:81]
	v_mfma_f32_16x16x32_bf16 v[74:77], v[160:163], v[210:213], v[74:77]
	v_mfma_f32_16x16x32_bf16 v[118:121], v[164:167], v[182:185], v[118:121]
	v_mfma_f32_16x16x32_bf16 v[114:117], v[172:175], v[182:185], v[114:117]
	v_mfma_f32_16x16x32_bf16 v[102:105], v[164:167], v[190:193], v[102:105]
	v_mfma_f32_16x16x32_bf16 v[98:101], v[172:175], v[190:193], v[98:101]
	v_mfma_f32_16x16x32_bf16 v[86:89], v[164:167], v[198:201], v[86:89]
	v_mfma_f32_16x16x32_bf16 v[82:85], v[172:175], v[198:201], v[82:85]
	v_mfma_f32_16x16x32_bf16 v[70:73], v[164:167], v[206:209], v[70:73]
	v_mfma_f32_16x16x32_bf16 v[66:69], v[172:175], v[206:209], v[66:69]
	v_mfma_f32_16x16x32_bf16 v[118:121], v[168:171], v[186:189], v[118:121]
	v_mfma_f32_16x16x32_bf16 v[114:117], v[176:179], v[186:189], v[114:117]
	v_mfma_f32_16x16x32_bf16 v[102:105], v[168:171], v[194:197], v[102:105]
	v_mfma_f32_16x16x32_bf16 v[98:101], v[176:179], v[194:197], v[98:101]
	v_mfma_f32_16x16x32_bf16 v[86:89], v[168:171], v[202:205], v[86:89]
	v_mfma_f32_16x16x32_bf16 v[82:85], v[176:179], v[202:205], v[82:85]
	v_mfma_f32_16x16x32_bf16 v[70:73], v[168:171], v[210:213], v[70:73]
	v_mfma_f32_16x16x32_bf16 v[66:69], v[176:179], v[210:213], v[66:69]
	s_setprio 0
	s_barrier
; #define PG8_STAGE(bufoff, gbase, voff) do { _Pragma("unroll") for (int _i = 0; _i < 2; ++_i) \
;         __builtin_amdgcn_global_load_lds((const unsigned*)((const char*)(gbase) + (voff)[_i]), (LAS unsigned*)(lds + (bufoff) + ldsw + _i * 8192), 16, 0, 0); } while (0)
; #define PG8_LDA(dst, b, h) do { _Pragma("unroll") for (int m = 0; m < 4; ++m) _Pragma("unroll") for (int k = 0; k < 2; ++k) dst[m][k] = *(const LAS bf16x8*)(lds + PG8_SA(b, h) + aoff + m * 2048 + k * 1024); } while (0)
; #define PG8_MMA(ai, bj, At, Bt) do { __builtin_amdgcn_s_setprio(1); _Pragma("unroll") for (int m = 0; m < 4; ++m) _Pragma("unroll") for (int n = 0; n < 2; ++n) _Pragma("unroll") for (int k = 0; k < 2; ++k) \
;         acc[ai][bj][m][n] = __builtin_amdgcn_mfma_f32_16x16x32_bf16(Bt[n][k], At[m][k], acc[ai][bj][m][n], 0, 0, 0); __builtin_amdgcn_s_setprio(0); } while (0)
; #define PG8_WAIT_V(n) asm volatile("s_waitcnt vmcnt(" #n ")" ::: "memory")
; #define PG8_WAIT_L(n) asm volatile("s_waitcnt lgkmcnt(" #n ")" ::: "memory")
; #define PG8_BAR __builtin_amdgcn_s_barrier()
; #define PG8_SCHED __builtin_amdgcn_sched_barrier(0)
; template <class Epi>
; __device__ __forceinline__ void gemm_phase(LAS unsigned char* lds, const Gemm g, const StaticOrder& S, const Epi& E) {
;     ...
;             PG8_LDA(At, 1, 1); PG8_STAGE(PG8_SB(1, 0), b3, voffB); PG8_STAGE(PG8_SB(1, 1), b3 + hstepB, voffB); PG8_STAGE(PG8_SA(1, 0), a3, voffA);
;             PG8_WAIT_V(8); PG8_WAIT_L(0); PG8_BAR; PG8_MMA(1, 0, At, B0); PG8_MMA(1, 1, At, B1); PG8_BAR; PG8_SCHED;
;         }
;         if (wr == 0) PG8_BAR;
	s_add_i32 s15, s15, s52
	v_lshl_add_u64 v[214:215], v[214:215], 0, s[34:35]
	s_mov_b32 m0, s15
	ds_read_b128 v[182:185], v159 offset:49152
	ds_read_b128 v[186:189], v159 offset:50176
	ds_read_b128 v[190:193], v159 offset:51200
	ds_read_b128 v[194:197], v159 offset:52224
	ds_read_b128 v[198:201], v159 offset:53248
	ds_read_b128 v[202:205], v159 offset:54272
	ds_read_b128 v[206:209], v159 offset:55296
	ds_read_b128 v[210:213], v159 offset:56320
	global_load_lds_dwordx4 v[214:215], off
	v_lshl_add_u64 v[214:215], v[216:217], 0, s[34:35]
	s_add_i32 m0, s15, 0x2000
	s_add_i32 s15, s17, s52
	global_load_lds_dwordx4 v[214:215], off
	v_lshl_add_u64 v[214:215], v[218:219], 0, s[34:35]
	s_mov_b32 m0, s15
	s_nop 0
	global_load_lds_dwordx4 v[214:215], off
	v_lshl_add_u64 v[214:215], v[220:221], 0, s[34:35]
	s_add_i32 m0, s15, 0x2000
	s_nop 0
	global_load_lds_dwordx4 v[214:215], off
	v_lshl_add_u64 v[214:215], v[222:223], 0, s[34:35]
	s_mov_b32 m0, s61
	s_nop 0
	global_load_lds_dwordx4 v[214:215], off
	v_lshl_add_u64 v[214:215], v[224:225], 0, s[34:35]
	s_mov_b32 m0, s80
	s_nop 0
	global_load_lds_dwordx4 v[214:215], off
	s_waitcnt vmcnt(8)
	s_waitcnt lgkmcnt(0)
	s_barrier
	s_setprio 1
	s_waitcnt lgkmcnt(0)
	v_mfma_f32_16x16x32_bf16 v[62:65], v[142:145], v[182:185], v[62:65]
	v_mfma_f32_16x16x32_bf16 v[58:61], v[150:153], v[182:185], v[58:61]
	v_mfma_f32_16x16x32_bf16 v[46:49], v[142:145], v[190:193], v[46:49]
	v_mfma_f32_16x16x32_bf16 v[42:45], v[150:153], v[190:193], v[42:45]
	v_mfma_f32_16x16x32_bf16 v[30:33], v[142:145], v[198:201], v[30:33]
	v_mfma_f32_16x16x32_bf16 v[26:29], v[150:153], v[198:201], v[26:29]
	v_mfma_f32_16x16x32_bf16 v[14:17], v[142:145], v[206:209], v[14:17]
	v_mfma_f32_16x16x32_bf16 v[10:13], v[150:153], v[206:209], v[10:13]
	v_mfma_f32_16x16x32_bf16 v[62:65], v[146:149], v[186:189], v[62:65]
	v_mfma_f32_16x16x32_bf16 v[58:61], v[160:163], v[186:189], v[58:61]
	v_mfma_f32_16x16x32_bf16 v[46:49], v[146:149], v[194:197], v[46:49]
	v_mfma_f32_16x16x32_bf16 v[42:45], v[160:163], v[194:197], v[42:45]
	v_mfma_f32_16x16x32_bf16 v[30:33], v[146:149], v[202:205], v[30:33]
	v_mfma_f32_16x16x32_bf16 v[26:29], v[160:163], v[202:205], v[26:29]
	v_mfma_f32_16x16x32_bf16 v[14:17], v[146:149], v[210:213], v[14:17]
	v_mfma_f32_16x16x32_bf16 v[10:13], v[160:163], v[210:213], v[10:13]
	v_mfma_f32_16x16x32_bf16 v[54:57], v[164:167], v[182:185], v[54:57]
	v_mfma_f32_16x16x32_bf16 v[50:53], v[172:175], v[182:185], v[50:53]
	v_mfma_f32_16x16x32_bf16 v[38:41], v[164:167], v[190:193], v[38:41]
	v_mfma_f32_16x16x32_bf16 v[34:37], v[172:175], v[190:193], v[34:37]
	v_mfma_f32_16x16x32_bf16 v[22:25], v[164:167], v[198:201], v[22:25]
	v_mfma_f32_16x16x32_bf16 v[18:21], v[172:175], v[198:201], v[18:21]
	v_mfma_f32_16x16x32_bf16 v[6:9], v[164:167], v[206:209], v[6:9]
	v_mfma_f32_16x16x32_bf16 v[2:5], v[172:175], v[206:209], v[2:5]
	v_mfma_f32_16x16x32_bf16 v[54:57], v[168:171], v[186:189], v[54:57]
	v_mfma_f32_16x16x32_bf16 v[50:53], v[176:179], v[186:189], v[50:53]
	v_mfma_f32_16x16x32_bf16 v[38:41], v[168:171], v[194:197], v[38:41]
	v_mfma_f32_16x16x32_bf16 v[34:37], v[176:179], v[194:197], v[34:37]
	v_mfma_f32_16x16x32_bf16 v[22:25], v[168:171], v[202:205], v[22:25]
	v_mfma_f32_16x16x32_bf16 v[18:21], v[176:179], v[202:205], v[18:21]
	v_mfma_f32_16x16x32_bf16 v[6:9], v[168:171], v[210:213], v[6:9]
	v_mfma_f32_16x16x32_bf16 v[2:5], v[176:179], v[210:213], v[2:5]
	s_setprio 0
	s_barrier
	s_add_u32 s13, s13, 0x100
	s_addc_u32 s14, s14, 0
	s_add_u32 s0, s0, 0x100
	s_addc_u32 s1, s1, 0
	s_cmp_ge_u32 s16, s31
	s_mov_b32 s15, s16
	s_cbranch_scc0 .LBB0_187
	s_and_b64 vcc, exec, s[88:89]
	s_cbranch_vccz .LBB0_190
	s_barrier

; #define PG8_STAGE(bufoff, gbase, voff) do { _Pragma("unroll") for (int _i = 0; _i < 2; ++_i) \
;         __builtin_amdgcn_global_load_lds((const unsigned*)((const char*)(gbase) + (voff)[_i]), (LAS unsigned*)(lds + (bufoff) + ldsw + _i * 8192), 16, 0, 0); } while (0)
; #define PG8_LDA(dst, b, h) do { _Pragma("unroll") for (int m = 0; m < 4; ++m) _Pragma("unroll") for (int k = 0; k < 2; ++k) dst[m][k] = *(const LAS bf16x8*)(lds + PG8_SA(b, h) + aoff + m * 2048 + k * 1024); } while (0)
; #define PG8_LDB(dst, b, h) do { _Pragma("unroll") for (int n = 0; n < 2; ++n) _Pragma("unroll") for (int k = 0; k < 2; ++k) dst[n][k] = *(const LAS bf16x8*)(lds + PG8_SB(b, h) + boff + n * 2048 + k * 1024); } while (0)
; #define PG8_MMA(ai, bj, At, Bt) do { __builtin_amdgcn_s_setprio(1); _Pragma("unroll") for (int m = 0; m < 4; ++m) _Pragma("unroll") for (int n = 0; n < 2; ++n) _Pragma("unroll") for (int k = 0; k < 2; ++k) \
;         acc[ai][bj][m][n] = __builtin_amdgcn_mfma_f32_16x16x32_bf16(Bt[n][k], At[m][k], acc[ai][bj][m][n], 0, 0, 0); __builtin_amdgcn_s_setprio(0); } while (0)
; #define PG8_WAIT_V(n) asm volatile("s_waitcnt vmcnt(" #n ")" ::: "memory")
; #define PG8_WAIT_L(n) asm volatile("s_waitcnt lgkmcnt(" #n ")" ::: "memory")
; #define PG8_BAR __builtin_amdgcn_s_barrier()
; #define PG8_SCHED __builtin_amdgcn_sched_barrier(0)
; template <class Epi>
; __device__ __forceinline__ void gemm_phase(LAS unsigned char* lds, const Gemm g, const StaticOrder& S, const Epi& E) {
;     ...
;             PG8_LDB(B0, 0, 0); PG8_LDB(B1, 0, 1); PG8_SCHED; PG8_LDA(At, 0, 0); PG8_STAGE(PG8_SA(1, 1), a1 + hstepA, voffA);
;             PG8_WAIT_V(8); PG8_WAIT_L(0); PG8_BAR; PG8_MMA(0, 0, At, B0); PG8_MMA(0, 1, At, B1); PG8_BAR; PG8_SCHED;
;             PG8_LDA(At, 0, 1); PG8_STAGE(PG8_SB(0, 0), b2, voffB); PG8_STAGE(PG8_SB(0, 1), b2 + hstepB, voffB); PG8_STAGE(PG8_SA(0, 0), a2, voffA);
;             PG8_WAIT_V(8); PG8_WAIT_L(0); PG8_BAR; PG8_MMA(1, 0, At, B0); PG8_MMA(1, 1, At, B1); PG8_BAR; PG8_SCHED;
.LBB0_308:
	s_add_i32 s50, s4, 2
	s_add_u32 s51, s0, 0x80
	s_addc_u32 s5, s1, 0
	s_add_i32 s61, 0, 0x10000
	s_cmp_eq_u32 s27, s4
	s_cselect_b32 s5, s95, s5
	s_cselect_b32 s4, s94, s51
	s_cselect_b32 s53, s97, s49
	s_cselect_b32 s52, s96, s48
	s_add_i32 s51, 0, 0x14000
	v_add_u32_e32 v142, s61, v237
	v_add_u32_e32 v158, s51, v237
	ds_read_b128 v[130:133], v142
	ds_read_b128 v[134:137], v142 offset:1024
	ds_read_b128 v[138:141], v142 offset:2048
	ds_read_b128 v[142:145], v142 offset:3072
	ds_read_b128 v[146:149], v158
	ds_read_b128 v[150:153], v158 offset:1024
	ds_read_b128 v[154:157], v158 offset:2048
	ds_read_b128 v[158:161], v158 offset:3072
	v_lshl_add_u64 v[178:179], s[0:1], 0, v[190:191]
	s_add_i32 m0, s19, 0xc000
	ds_read_b128 v[162:165], v243
	ds_read_b128 v[166:169], v243 offset:1024
	ds_read_b128 v[170:173], v243 offset:2048
	ds_read_b128 v[174:177], v243 offset:3072
	ds_read_b128 v[192:195], v243 offset:4096
	ds_read_b128 v[196:199], v243 offset:5120
	ds_read_b128 v[200:203], v243 offset:6144
	ds_read_b128 v[204:207], v243 offset:7168
	global_load_lds_dwordx4 v[178:179], off
	v_lshl_add_u64 v[178:179], s[0:1], 0, v[188:189]
	s_add_i32 m0, s19, 0xe000
	s_nop 0
	global_load_lds_dwordx4 v[178:179], off
	s_waitcnt vmcnt(8)
	s_waitcnt lgkmcnt(0)
	s_barrier
	s_setprio 1
	s_waitcnt lgkmcnt(0)
	v_mfma_f32_16x16x32_bf16 v[126:129], v[130:133], v[162:165], v[126:129]
	v_mfma_f32_16x16x32_bf16 v[122:125], v[138:141], v[162:165], v[122:125]
	v_mfma_f32_16x16x32_bf16 v[118:121], v[130:133], v[170:173], v[118:121]
	v_mfma_f32_16x16x32_bf16 v[114:117], v[138:141], v[170:173], v[114:117]
	v_mfma_f32_16x16x32_bf16 v[110:113], v[130:133], v[192:195], v[110:113]
	v_mfma_f32_16x16x32_bf16 v[106:109], v[138:141], v[192:195], v[106:109]
	v_mfma_f32_16x16x32_bf16 v[102:105], v[130:133], v[200:203], v[102:105]
	v_mfma_f32_16x16x32_bf16 v[98:101], v[138:141], v[200:203], v[98:101]
	v_mfma_f32_16x16x32_bf16 v[126:129], v[134:137], v[166:169], v[126:129]
	v_mfma_f32_16x16x32_bf16 v[122:125], v[142:145], v[166:169], v[122:125]
	v_mfma_f32_16x16x32_bf16 v[118:121], v[134:137], v[174:177], v[118:121]
	v_mfma_f32_16x16x32_bf16 v[114:117], v[142:145], v[174:177], v[114:117]
	v_mfma_f32_16x16x32_bf16 v[110:113], v[134:137], v[196:199], v[110:113]
	v_mfma_f32_16x16x32_bf16 v[106:109], v[142:145], v[196:199], v[106:109]
	v_mfma_f32_16x16x32_bf16 v[102:105], v[134:137], v[204:207], v[102:105]
	v_mfma_f32_16x16x32_bf16 v[98:101], v[142:145], v[204:207], v[98:101]
	v_mfma_f32_16x16x32_bf16 v[94:97], v[146:149], v[162:165], v[94:97]
	v_mfma_f32_16x16x32_bf16 v[90:93], v[154:157], v[162:165], v[90:93]
	v_mfma_f32_16x16x32_bf16 v[86:89], v[146:149], v[170:173], v[86:89]
	v_mfma_f32_16x16x32_bf16 v[82:85], v[154:157], v[170:173], v[82:85]
	v_mfma_f32_16x16x32_bf16 v[78:81], v[146:149], v[192:195], v[78:81]
	v_mfma_f32_16x16x32_bf16 v[74:77], v[154:157], v[192:195], v[74:77]
	v_mfma_f32_16x16x32_bf16 v[70:73], v[146:149], v[200:203], v[70:73]
	v_mfma_f32_16x16x32_bf16 v[66:69], v[154:157], v[200:203], v[66:69]
	v_mfma_f32_16x16x32_bf16 v[94:97], v[150:153], v[166:169], v[94:97]
	v_mfma_f32_16x16x32_bf16 v[90:93], v[158:161], v[166:169], v[90:93]
	v_mfma_f32_16x16x32_bf16 v[86:89], v[150:153], v[174:177], v[86:89]
	v_mfma_f32_16x16x32_bf16 v[82:85], v[158:161], v[174:177], v[82:85]
	v_mfma_f32_16x16x32_bf16 v[78:81], v[150:153], v[196:199], v[78:81]
	v_mfma_f32_16x16x32_bf16 v[74:77], v[158:161], v[196:199], v[74:77]
	v_mfma_f32_16x16x32_bf16 v[70:73], v[150:153], v[204:207], v[70:73]
	v_mfma_f32_16x16x32_bf16 v[66:69], v[158:161], v[204:207], v[66:69]
	s_setprio 0
	s_barrier
	s_add_i32 s61, s61, s16
	v_lshl_add_u64 v[178:179], s[52:53], 0, v[0:1]
	s_mov_b32 m0, s61
	ds_read_b128 v[162:165], v243 offset:16384
	ds_read_b128 v[166:169], v243 offset:17408
	ds_read_b128 v[170:173], v243 offset:18432
	ds_read_b128 v[174:177], v243 offset:19456
	ds_read_b128 v[192:195], v243 offset:20480
	ds_read_b128 v[196:199], v243 offset:21504
	ds_read_b128 v[200:203], v243 offset:22528
	ds_read_b128 v[204:207], v243 offset:23552
	global_load_lds_dwordx4 v[178:179], off
	s_add_i32 m0, s61, 0x2000
	v_lshl_add_u64 v[208:209], s[52:53], 0, v[186:187]
	s_add_u32 s52, s52, s46
	s_addc_u32 s53, s53, 0
	s_add_i32 s51, s51, s16
	global_load_lds_dwordx4 v[208:209], off
	v_lshl_add_u64 v[210:211], s[52:53], 0, v[0:1]
	s_mov_b32 m0, s51
	v_lshl_add_u64 v[212:213], s[52:53], 0, v[186:187]
	global_load_lds_dwordx4 v[210:211], off
	s_add_i32 m0, s51, 0x2000
	v_lshl_add_u64 v[214:215], s[4:5], 0, v[182:183]
	global_load_lds_dwordx4 v[212:213], off
	s_mov_b32 m0, s19
	v_lshl_add_u64 v[216:217], s[4:5], 0, v[184:185]
	global_load_lds_dwordx4 v[214:215], off
	s_mov_b32 m0, s20
	s_nop 0
	global_load_lds_dwordx4 v[216:217], off
	s_waitcnt vmcnt(8)
	s_waitcnt lgkmcnt(0)
	s_barrier
; #define PG8_STAGE(bufoff, gbase, voff) do { _Pragma("unroll") for (int _i = 0; _i < 2; ++_i) \
;         __builtin_amdgcn_global_load_lds((const unsigned*)((const char*)(gbase) + (voff)[_i]), (LAS unsigned*)(lds + (bufoff) + ldsw + _i * 8192), 16, 0, 0); } while (0)
; #define PG8_LDA(dst, b, h) do { _Pragma("unroll") for (int m = 0; m < 4; ++m) _Pragma("unroll") for (int k = 0; k < 2; ++k) dst[m][k] = *(const LAS bf16x8*)(lds + PG8_SA(b, h) + aoff + m * 2048 + k * 1024); } while (0)
; #define PG8_LDB(dst, b, h) do { _Pragma("unroll") for (int n = 0; n < 2; ++n) _Pragma("unroll") for (int k = 0; k < 2; ++k) dst[n][k] = *(const LAS bf16x8*)(lds + PG8_SB(b, h) + boff + n * 2048 + k * 1024); } while (0)
; #define PG8_MMA(ai, bj, At, Bt) do { __builtin_amdgcn_s_setprio(1); _Pragma("unroll") for (int m = 0; m < 4; ++m) _Pragma("unroll") for (int n = 0; n < 2; ++n) _Pragma("unroll") for (int k = 0; k < 2; ++k) \
;         acc[ai][bj][m][n] = __builtin_amdgcn_mfma_f32_16x16x32_bf16(Bt[n][k], At[m][k], acc[ai][bj][m][n], 0, 0, 0); __builtin_amdgcn_s_setprio(0); } while (0)
; #define PG8_WAIT_V(n) asm volatile("s_waitcnt vmcnt(" #n ")" ::: "memory")
; #define PG8_WAIT_L(n) asm volatile("s_waitcnt lgkmcnt(" #n ")" ::: "memory")
; #define PG8_BAR __builtin_amdgcn_s_barrier()
; #define PG8_SCHED __builtin_amdgcn_sched_barrier(0)
; template <class Epi>
; __device__ __forceinline__ void gemm_phase(LAS unsigned char* lds, const Gemm g, const StaticOrder& S, const Epi& E) {
;     ...
;             PG8_WAIT_V(8); PG8_WAIT_L(0); PG8_BAR; PG8_MMA(1, 0, At, B0); PG8_MMA(1, 1, At, B1); PG8_BAR; PG8_SCHED;
;             PG8_LDB(B0, 1, 0); PG8_LDB(B1, 1, 1); PG8_SCHED; PG8_LDA(At, 1, 0); PG8_STAGE(PG8_SA(0, 1), a2 + hstepA, voffA);
;             PG8_WAIT_V(8); PG8_WAIT_L(0); PG8_BAR; PG8_MMA(0, 0, At, B0); PG8_MMA(0, 1, At, B1); PG8_BAR; PG8_SCHED;
	s_setprio 1
	s_waitcnt lgkmcnt(0)
	v_mfma_f32_16x16x32_bf16 v[62:65], v[130:133], v[162:165], v[62:65]
	v_mfma_f32_16x16x32_bf16 v[58:61], v[138:141], v[162:165], v[58:61]
	v_mfma_f32_16x16x32_bf16 v[54:57], v[130:133], v[170:173], v[54:57]
	v_mfma_f32_16x16x32_bf16 v[50:53], v[138:141], v[170:173], v[50:53]
	v_mfma_f32_16x16x32_bf16 v[46:49], v[130:133], v[192:195], v[46:49]
	v_mfma_f32_16x16x32_bf16 v[42:45], v[138:141], v[192:195], v[42:45]
	v_mfma_f32_16x16x32_bf16 v[38:41], v[130:133], v[200:203], v[38:41]
	v_mfma_f32_16x16x32_bf16 v[34:37], v[138:141], v[200:203], v[34:37]
	v_mfma_f32_16x16x32_bf16 v[62:65], v[134:137], v[166:169], v[62:65]
	v_mfma_f32_16x16x32_bf16 v[58:61], v[142:145], v[166:169], v[58:61]
	v_mfma_f32_16x16x32_bf16 v[54:57], v[134:137], v[174:177], v[54:57]
	v_mfma_f32_16x16x32_bf16 v[50:53], v[142:145], v[174:177], v[50:53]
	v_mfma_f32_16x16x32_bf16 v[46:49], v[134:137], v[196:199], v[46:49]
	v_mfma_f32_16x16x32_bf16 v[42:45], v[142:145], v[196:199], v[42:45]
	v_mfma_f32_16x16x32_bf16 v[38:41], v[134:137], v[204:207], v[38:41]
	v_mfma_f32_16x16x32_bf16 v[34:37], v[142:145], v[204:207], v[34:37]
	v_mfma_f32_16x16x32_bf16 v[30:33], v[146:149], v[162:165], v[30:33]
	v_mfma_f32_16x16x32_bf16 v[26:29], v[154:157], v[162:165], v[26:29]
	v_mfma_f32_16x16x32_bf16 v[22:25], v[146:149], v[170:173], v[22:25]
	v_mfma_f32_16x16x32_bf16 v[18:21], v[154:157], v[170:173], v[18:21]
	v_mfma_f32_16x16x32_bf16 v[14:17], v[146:149], v[192:195], v[14:17]
	v_mfma_f32_16x16x32_bf16 v[10:13], v[154:157], v[192:195], v[10:13]
	v_mfma_f32_16x16x32_bf16 v[6:9], v[146:149], v[200:203], v[6:9]
	v_mfma_f32_16x16x32_bf16 v[2:5], v[154:157], v[200:203], v[2:5]
	v_mfma_f32_16x16x32_bf16 v[30:33], v[150:153], v[166:169], v[30:33]
	v_mfma_f32_16x16x32_bf16 v[26:29], v[158:161], v[166:169], v[26:29]
	v_mfma_f32_16x16x32_bf16 v[22:25], v[150:153], v[174:177], v[22:25]
	v_mfma_f32_16x16x32_bf16 v[18:21], v[158:161], v[174:177], v[18:21]
	v_mfma_f32_16x16x32_bf16 v[14:17], v[150:153], v[196:199], v[14:17]
	v_mfma_f32_16x16x32_bf16 v[10:13], v[158:161], v[196:199], v[10:13]
	v_mfma_f32_16x16x32_bf16 v[6:9], v[150:153], v[204:207], v[6:9]
	v_mfma_f32_16x16x32_bf16 v[2:5], v[158:161], v[204:207], v[2:5]
	s_setprio 0
	s_barrier
	s_add_i32 s51, 0, 0x18000
	s_add_i32 s52, 0, 0x1c000
	v_add_u32_e32 v142, s51, v237
	v_add_u32_e32 v158, s52, v237
	ds_read_b128 v[130:133], v142
	ds_read_b128 v[134:137], v142 offset:1024
	ds_read_b128 v[138:141], v142 offset:2048
	ds_read_b128 v[142:145], v142 offset:3072
	ds_read_b128 v[146:149], v158
	ds_read_b128 v[150:153], v158 offset:1024
	ds_read_b128 v[154:157], v158 offset:2048
	ds_read_b128 v[158:161], v158 offset:3072
	s_add_u32 s4, s4, s46
	s_addc_u32 s5, s5, 0
	s_mov_b32 m0, s21
	v_lshl_add_u64 v[218:219], s[4:5], 0, v[182:183]
	ds_read_b128 v[162:165], v243 offset:32768
	ds_read_b128 v[166:169], v243 offset:33792
	ds_read_b128 v[170:173], v243 offset:34816
	ds_read_b128 v[174:177], v243 offset:35840
	ds_read_b128 v[192:195], v243 offset:36864
	ds_read_b128 v[196:199], v243 offset:37888
	ds_read_b128 v[200:203], v243 offset:38912
	ds_read_b128 v[204:207], v243 offset:39936
	global_load_lds_dwordx4 v[218:219], off
	v_lshl_add_u64 v[218:219], s[4:5], 0, v[184:185]
	s_mov_b32 m0, s22
	s_nop 0
	global_load_lds_dwordx4 v[218:219], off
	s_waitcnt vmcnt(8)
	s_waitcnt lgkmcnt(0)
	s_barrier
	s_setprio 1
	s_waitcnt lgkmcnt(0)
	v_mfma_f32_16x16x32_bf16 v[126:129], v[130:133], v[162:165], v[126:129]
	v_mfma_f32_16x16x32_bf16 v[122:125], v[138:141], v[162:165], v[122:125]
	v_mfma_f32_16x16x32_bf16 v[118:121], v[130:133], v[170:173], v[118:121]
	v_mfma_f32_16x16x32_bf16 v[114:117], v[138:141], v[170:173], v[114:117]
	v_mfma_f32_16x16x32_bf16 v[110:113], v[130:133], v[192:195], v[110:113]
	v_mfma_f32_16x16x32_bf16 v[106:109], v[138:141], v[192:195], v[106:109]
	v_mfma_f32_16x16x32_bf16 v[102:105], v[130:133], v[200:203], v[102:105]
	v_mfma_f32_16x16x32_bf16 v[98:101], v[138:141], v[200:203], v[98:101]
	v_mfma_f32_16x16x32_bf16 v[126:129], v[134:137], v[166:169], v[126:129]
	v_mfma_f32_16x16x32_bf16 v[122:125], v[142:145], v[166:169], v[122:125]
	v_mfma_f32_16x16x32_bf16 v[118:121], v[134:137], v[174:177], v[118:121]
	v_mfma_f32_16x16x32_bf16 v[114:117], v[142:145], v[174:177], v[114:117]
	v_mfma_f32_16x16x32_bf16 v[110:113], v[134:137], v[196:199], v[110:113]
	v_mfma_f32_16x16x32_bf16 v[106:109], v[142:145], v[196:199], v[106:109]
	v_mfma_f32_16x16x32_bf16 v[102:105], v[134:137], v[204:207], v[102:105]
	v_mfma_f32_16x16x32_bf16 v[98:101], v[142:145], v[204:207], v[98:101]
	v_mfma_f32_16x16x32_bf16 v[94:97], v[146:149], v[162:165], v[94:97]
	v_mfma_f32_16x16x32_bf16 v[90:93], v[154:157], v[162:165], v[90:93]
	v_mfma_f32_16x16x32_bf16 v[86:89], v[146:149], v[170:173], v[86:89]
	v_mfma_f32_16x16x32_bf16 v[82:85], v[154:157], v[170:173], v[82:85]
	v_mfma_f32_16x16x32_bf16 v[78:81], v[146:149], v[192:195], v[78:81]
	v_mfma_f32_16x16x32_bf16 v[74:77], v[154:157], v[192:195], v[74:77]
	v_mfma_f32_16x16x32_bf16 v[70:73], v[146:149], v[200:203], v[70:73]
	v_mfma_f32_16x16x32_bf16 v[66:69], v[154:157], v[200:203], v[66:69]
	v_mfma_f32_16x16x32_bf16 v[94:97], v[150:153], v[166:169], v[94:97]
	v_mfma_f32_16x16x32_bf16 v[90:93], v[158:161], v[166:169], v[90:93]
	v_mfma_f32_16x16x32_bf16 v[86:89], v[150:153], v[174:177], v[86:89]
	v_mfma_f32_16x16x32_bf16 v[82:85], v[158:161], v[174:177], v[82:85]
	v_mfma_f32_16x16x32_bf16 v[78:81], v[150:153], v[196:199], v[78:81]
	v_mfma_f32_16x16x32_bf16 v[74:77], v[158:161], v[196:199], v[74:77]
	v_mfma_f32_16x16x32_bf16 v[70:73], v[150:153], v[204:207], v[70:73]
	v_mfma_f32_16x16x32_bf16 v[66:69], v[158:161], v[204:207], v[66:69]
	s_setprio 0
	s_barrier
; #define PG8_STAGE(bufoff, gbase, voff) do { _Pragma("unroll") for (int _i = 0; _i < 2; ++_i) \
;         __builtin_amdgcn_global_load_lds((const unsigned*)((const char*)(gbase) + (voff)[_i]), (LAS unsigned*)(lds + (bufoff) + ldsw + _i * 8192), 16, 0, 0); } while (0)
; #define PG8_LDA(dst, b, h) do { _Pragma("unroll") for (int m = 0; m < 4; ++m) _Pragma("unroll") for (int k = 0; k < 2; ++k) dst[m][k] = *(const LAS bf16x8*)(lds + PG8_SA(b, h) + aoff + m * 2048 + k * 1024); } while (0)
; #define PG8_MMA(ai, bj, At, Bt) do { __builtin_amdgcn_s_setprio(1); _Pragma("unroll") for (int m = 0; m < 4; ++m) _Pragma("unroll") for (int n = 0; n < 2; ++n) _Pragma("unroll") for (int k = 0; k < 2; ++k) \
;         acc[ai][bj][m][n] = __builtin_amdgcn_mfma_f32_16x16x32_bf16(Bt[n][k], At[m][k], acc[ai][bj][m][n], 0, 0, 0); __builtin_amdgcn_s_setprio(0); } while (0)
; #define PG8_WAIT_V(n) asm volatile("s_waitcnt vmcnt(" #n ")" ::: "memory")
; #define PG8_WAIT_L(n) asm volatile("s_waitcnt lgkmcnt(" #n ")" ::: "memory")
; #define PG8_BAR __builtin_amdgcn_s_barrier()
; #define PG8_SCHED __builtin_amdgcn_sched_barrier(0)
; template <class Epi>
; __device__ __forceinline__ void gemm_phase(LAS unsigned char* lds, const Gemm g, const StaticOrder& S, const Epi& E) {
;     ...
;             PG8_LDA(At, 1, 1); PG8_STAGE(PG8_SB(1, 0), b3, voffB); PG8_STAGE(PG8_SB(1, 1), b3 + hstepB, voffB); PG8_STAGE(PG8_SA(1, 0), a3, voffA);
;             PG8_WAIT_V(8); PG8_WAIT_L(0); PG8_BAR; PG8_MMA(1, 0, At, B0); PG8_MMA(1, 1, At, B1); PG8_BAR; PG8_SCHED;
;         }
;         if (wr == 0) PG8_BAR;
	s_add_i32 s4, s51, s16
	v_lshl_add_u64 v[178:179], v[178:179], 0, s[34:35]
	s_mov_b32 m0, s4
	ds_read_b128 v[162:165], v243 offset:49152
	ds_read_b128 v[166:169], v243 offset:50176
	ds_read_b128 v[170:173], v243 offset:51200
	ds_read_b128 v[174:177], v243 offset:52224
	ds_read_b128 v[192:195], v243 offset:53248
	ds_read_b128 v[196:199], v243 offset:54272
	ds_read_b128 v[200:203], v243 offset:55296
	ds_read_b128 v[204:207], v243 offset:56320
	global_load_lds_dwordx4 v[178:179], off
	v_lshl_add_u64 v[178:179], v[208:209], 0, s[34:35]
	s_add_i32 m0, s4, 0x2000
	s_add_i32 s4, s52, s16
	global_load_lds_dwordx4 v[178:179], off
	v_lshl_add_u64 v[178:179], v[210:211], 0, s[34:35]
	s_mov_b32 m0, s4
	s_nop 0
	global_load_lds_dwordx4 v[178:179], off
	v_lshl_add_u64 v[178:179], v[212:213], 0, s[34:35]
	s_add_i32 m0, s4, 0x2000
	s_nop 0
	global_load_lds_dwordx4 v[178:179], off
	v_lshl_add_u64 v[178:179], v[214:215], 0, s[34:35]
	s_mov_b32 m0, s25
	s_nop 0
	global_load_lds_dwordx4 v[178:179], off
	v_lshl_add_u64 v[178:179], v[216:217], 0, s[34:35]
	s_mov_b32 m0, s26
	s_nop 0
	global_load_lds_dwordx4 v[178:179], off
	s_waitcnt vmcnt(8)
	s_waitcnt lgkmcnt(0)
	s_barrier
	s_setprio 1
	s_waitcnt lgkmcnt(0)
	v_mfma_f32_16x16x32_bf16 v[62:65], v[130:133], v[162:165], v[62:65]
	v_mfma_f32_16x16x32_bf16 v[58:61], v[138:141], v[162:165], v[58:61]
	v_mfma_f32_16x16x32_bf16 v[54:57], v[130:133], v[170:173], v[54:57]
	v_mfma_f32_16x16x32_bf16 v[50:53], v[138:141], v[170:173], v[50:53]
	v_mfma_f32_16x16x32_bf16 v[46:49], v[130:133], v[192:195], v[46:49]
	v_mfma_f32_16x16x32_bf16 v[42:45], v[138:141], v[192:195], v[42:45]
	v_mfma_f32_16x16x32_bf16 v[38:41], v[130:133], v[200:203], v[38:41]
	v_mfma_f32_16x16x32_bf16 v[34:37], v[138:141], v[200:203], v[34:37]
	v_mfma_f32_16x16x32_bf16 v[62:65], v[134:137], v[166:169], v[62:65]
	v_mfma_f32_16x16x32_bf16 v[58:61], v[142:145], v[166:169], v[58:61]
	v_mfma_f32_16x16x32_bf16 v[54:57], v[134:137], v[174:177], v[54:57]
	v_mfma_f32_16x16x32_bf16 v[50:53], v[142:145], v[174:177], v[50:53]
	v_mfma_f32_16x16x32_bf16 v[46:49], v[134:137], v[196:199], v[46:49]
	v_mfma_f32_16x16x32_bf16 v[42:45], v[142:145], v[196:199], v[42:45]
	v_mfma_f32_16x16x32_bf16 v[38:41], v[134:137], v[204:207], v[38:41]
	v_mfma_f32_16x16x32_bf16 v[34:37], v[142:145], v[204:207], v[34:37]
	v_mfma_f32_16x16x32_bf16 v[30:33], v[146:149], v[162:165], v[30:33]
	v_mfma_f32_16x16x32_bf16 v[26:29], v[154:157], v[162:165], v[26:29]
	v_mfma_f32_16x16x32_bf16 v[22:25], v[146:149], v[170:173], v[22:25]
	v_mfma_f32_16x16x32_bf16 v[18:21], v[154:157], v[170:173], v[18:21]
	v_mfma_f32_16x16x32_bf16 v[14:17], v[146:149], v[192:195], v[14:17]
	v_mfma_f32_16x16x32_bf16 v[10:13], v[154:157], v[192:195], v[10:13]
	v_mfma_f32_16x16x32_bf16 v[6:9], v[146:149], v[200:203], v[6:9]
	v_mfma_f32_16x16x32_bf16 v[2:5], v[154:157], v[200:203], v[2:5]
	v_mfma_f32_16x16x32_bf16 v[30:33], v[150:153], v[166:169], v[30:33]
	v_mfma_f32_16x16x32_bf16 v[26:29], v[158:161], v[166:169], v[26:29]
	v_mfma_f32_16x16x32_bf16 v[22:25], v[150:153], v[174:177], v[22:25]
	v_mfma_f32_16x16x32_bf16 v[18:21], v[158:161], v[174:177], v[18:21]
	v_mfma_f32_16x16x32_bf16 v[14:17], v[150:153], v[196:199], v[14:17]
	v_mfma_f32_16x16x32_bf16 v[10:13], v[158:161], v[196:199], v[10:13]
	v_mfma_f32_16x16x32_bf16 v[6:9], v[150:153], v[204:207], v[6:9]
	v_mfma_f32_16x16x32_bf16 v[2:5], v[158:161], v[204:207], v[2:5]
	s_setprio 0
	s_barrier
	s_add_u32 s48, s48, 0x100
	s_addc_u32 s49, s49, 0
	s_add_u32 s0, s0, 0x100
	s_addc_u32 s1, s1, 0
	s_cmp_ge_u32 s50, s24
	s_mov_b32 s4, s50
	s_cbranch_scc0 .LBB0_308
	s_and_b64 vcc, exec, s[88:89]
	s_cbranch_vccz .LBB0_311
	s_barrier

; #define PG8_STAGE(bufoff, gbase, voff) do { _Pragma("unroll") for (int _i = 0; _i < 2; ++_i) \
;         __builtin_amdgcn_global_load_lds((const unsigned*)((const char*)(gbase) + (voff)[_i]), (LAS unsigned*)(lds + (bufoff) + ldsw + _i * 8192), 16, 0, 0); } while (0)
; #define PG8_LDA(dst, b, h) do { _Pragma("unroll") for (int m = 0; m < 4; ++m) _Pragma("unroll") for (int k = 0; k < 2; ++k) dst[m][k] = *(const LAS bf16x8*)(lds + PG8_SA(b, h) + aoff + m * 2048 + k * 1024); } while (0)
; #define PG8_LDB(dst, b, h) do { _Pragma("unroll") for (int n = 0; n < 2; ++n) _Pragma("unroll") for (int k = 0; k < 2; ++k) dst[n][k] = *(const LAS bf16x8*)(lds + PG8_SB(b, h) + boff + n * 2048 + k * 1024); } while (0)
; #define PG8_MMA(ai, bj, At, Bt) do { __builtin_amdgcn_s_setprio(1); _Pragma("unroll") for (int m = 0; m < 4; ++m) _Pragma("unroll") for (int n = 0; n < 2; ++n) _Pragma("unroll") for (int k = 0; k < 2; ++k) \
;         acc[ai][bj][m][n] = __builtin_amdgcn_mfma_f32_16x16x32_bf16(Bt[n][k], At[m][k], acc[ai][bj][m][n], 0, 0, 0); __builtin_amdgcn_s_setprio(0); } while (0)
; #define PG8_WAIT_V(n) asm volatile("s_waitcnt vmcnt(" #n ")" ::: "memory")
; #define PG8_WAIT_L(n) asm volatile("s_waitcnt lgkmcnt(" #n ")" ::: "memory")
; #define PG8_BAR __builtin_amdgcn_s_barrier()
; #define PG8_SCHED __builtin_amdgcn_sched_barrier(0)
; template <class Epi>
; __device__ __forceinline__ void gemm_phase(LAS unsigned char* lds, const Gemm g, const StaticOrder& S, const Epi& E) {
;     ...
;             PG8_LDB(B0, 0, 0); PG8_LDB(B1, 0, 1); PG8_SCHED; PG8_LDA(At, 0, 0); PG8_STAGE(PG8_SA(1, 1), a1 + hstepA, voffA);
;             PG8_WAIT_V(8); PG8_WAIT_L(0); PG8_BAR; PG8_MMA(0, 0, At, B0); PG8_MMA(0, 1, At, B1); PG8_BAR; PG8_SCHED;
;             PG8_LDA(At, 0, 1); PG8_STAGE(PG8_SB(0, 0), b2, voffB); PG8_STAGE(PG8_SB(0, 1), b2 + hstepB, voffB); PG8_STAGE(PG8_SA(0, 0), a2, voffA);
;             PG8_WAIT_V(8); PG8_WAIT_L(0); PG8_BAR; PG8_MMA(1, 0, At, B0); PG8_MMA(1, 1, At, B1); PG8_BAR; PG8_SCHED;
.LBB0_355:
	s_add_u32 s42, s40, 0x100
	s_addc_u32 s43, s41, 0
	s_add_i32 s51, 0, 0x10000
	s_cmp_eq_u32 s50, 12
	s_cselect_b32 s49, s1, s43
	s_cselect_b32 s48, s5, s42
	v_add_u32_e32 v0, s51, v156
	s_cselect_b32 s45, s26, s46
	s_cselect_b32 s44, s27, s31
	s_add_i32 s52, 0, 0x14000
	ds_read_b128 v[130:133], v0
	ds_read_b128 v[134:137], v0 offset:1024
	ds_read_b128 v[150:153], v0 offset:2048
	ds_read_b128 v[158:161], v0 offset:3072
	v_add_u32_e32 v0, s52, v156
	ds_read_b128 v[162:165], v0
	ds_read_b128 v[166:169], v0 offset:1024
	ds_read_b128 v[170:173], v0 offset:2048
	ds_read_b128 v[174:177], v0 offset:3072
	v_lshl_add_u64 v[178:179], s[40:41], 0, v[148:149]
	s_add_i32 m0, s13, 0xc000
	ds_read_b128 v[182:185], v157
	ds_read_b128 v[186:189], v157 offset:1024
	ds_read_b128 v[190:193], v157 offset:2048
	ds_read_b128 v[194:197], v157 offset:3072
	ds_read_b128 v[198:201], v157 offset:4096
	ds_read_b128 v[202:205], v157 offset:5120
	ds_read_b128 v[206:209], v157 offset:6144
	ds_read_b128 v[210:213], v157 offset:7168
	global_load_lds_dwordx4 v[178:179], off
	v_lshl_add_u64 v[178:179], s[40:41], 0, v[146:147]
	s_add_i32 m0, s13, 0xe000
	s_nop 0
	global_load_lds_dwordx4 v[178:179], off
	s_waitcnt vmcnt(8)
	s_waitcnt lgkmcnt(0)
	s_barrier
	s_setprio 1
	s_waitcnt lgkmcnt(0)
	v_mfma_f32_16x16x32_bf16 v[126:129], v[130:133], v[182:185], v[126:129]
	v_mfma_f32_16x16x32_bf16 v[122:125], v[150:153], v[182:185], v[122:125]
	v_mfma_f32_16x16x32_bf16 v[118:121], v[130:133], v[190:193], v[118:121]
	v_mfma_f32_16x16x32_bf16 v[114:117], v[150:153], v[190:193], v[114:117]
	v_mfma_f32_16x16x32_bf16 v[110:113], v[130:133], v[198:201], v[110:113]
	v_mfma_f32_16x16x32_bf16 v[106:109], v[150:153], v[198:201], v[106:109]
	v_mfma_f32_16x16x32_bf16 v[102:105], v[130:133], v[206:209], v[102:105]
	v_mfma_f32_16x16x32_bf16 v[98:101], v[150:153], v[206:209], v[98:101]
	v_mfma_f32_16x16x32_bf16 v[126:129], v[134:137], v[186:189], v[126:129]
	v_mfma_f32_16x16x32_bf16 v[122:125], v[158:161], v[186:189], v[122:125]
	v_mfma_f32_16x16x32_bf16 v[118:121], v[134:137], v[194:197], v[118:121]
	v_mfma_f32_16x16x32_bf16 v[114:117], v[158:161], v[194:197], v[114:117]
	v_mfma_f32_16x16x32_bf16 v[110:113], v[134:137], v[202:205], v[110:113]
	v_mfma_f32_16x16x32_bf16 v[106:109], v[158:161], v[202:205], v[106:109]
	v_mfma_f32_16x16x32_bf16 v[102:105], v[134:137], v[210:213], v[102:105]
	v_mfma_f32_16x16x32_bf16 v[98:101], v[158:161], v[210:213], v[98:101]
	v_mfma_f32_16x16x32_bf16 v[62:65], v[162:165], v[182:185], v[62:65]
	v_mfma_f32_16x16x32_bf16 v[58:61], v[170:173], v[182:185], v[58:61]
	v_mfma_f32_16x16x32_bf16 v[54:57], v[162:165], v[190:193], v[54:57]
	v_mfma_f32_16x16x32_bf16 v[50:53], v[170:173], v[190:193], v[50:53]
	v_mfma_f32_16x16x32_bf16 v[46:49], v[162:165], v[198:201], v[46:49]
	v_mfma_f32_16x16x32_bf16 v[42:45], v[170:173], v[198:201], v[42:45]
	v_mfma_f32_16x16x32_bf16 v[38:41], v[162:165], v[206:209], v[38:41]
	v_mfma_f32_16x16x32_bf16 v[34:37], v[170:173], v[206:209], v[34:37]
	v_mfma_f32_16x16x32_bf16 v[62:65], v[166:169], v[186:189], v[62:65]
	v_mfma_f32_16x16x32_bf16 v[58:61], v[174:177], v[186:189], v[58:61]
	v_mfma_f32_16x16x32_bf16 v[54:57], v[166:169], v[194:197], v[54:57]
	v_mfma_f32_16x16x32_bf16 v[50:53], v[174:177], v[194:197], v[50:53]
	v_mfma_f32_16x16x32_bf16 v[46:49], v[166:169], v[202:205], v[46:49]
	v_mfma_f32_16x16x32_bf16 v[42:45], v[174:177], v[202:205], v[42:45]
	v_mfma_f32_16x16x32_bf16 v[38:41], v[166:169], v[210:213], v[38:41]
	v_mfma_f32_16x16x32_bf16 v[34:37], v[174:177], v[210:213], v[34:37]
	s_setprio 0
	s_barrier
	s_add_i32 s40, s51, s12
	v_lshl_add_u64 v[178:179], s[44:45], 0, v[140:141]
	s_mov_b32 m0, s40
	ds_read_b128 v[182:185], v157 offset:16384
	ds_read_b128 v[186:189], v157 offset:17408
	ds_read_b128 v[190:193], v157 offset:18432
	ds_read_b128 v[194:197], v157 offset:19456
	ds_read_b128 v[198:201], v157 offset:20480
	ds_read_b128 v[202:205], v157 offset:21504
	ds_read_b128 v[206:209], v157 offset:22528
	ds_read_b128 v[210:213], v157 offset:23552
	global_load_lds_dwordx4 v[178:179], off
	s_add_i32 m0, s40, 0x2000
	s_add_u32 s40, s44, 0x40000
	v_lshl_add_u64 v[214:215], s[44:45], 0, v[144:145]
	s_addc_u32 s41, s45, 0
	s_add_i32 s51, s52, s12
	global_load_lds_dwordx4 v[214:215], off
	v_lshl_add_u64 v[216:217], s[40:41], 0, v[140:141]
	s_mov_b32 m0, s51
	v_lshl_add_u64 v[218:219], s[48:49], 0, v[142:143]
	global_load_lds_dwordx4 v[216:217], off
	v_lshl_add_u64 v[216:217], s[40:41], 0, v[144:145]
	s_add_i32 m0, s51, 0x2000
	s_nop 0
	global_load_lds_dwordx4 v[216:217], off
	v_lshl_add_u64 v[216:217], s[48:49], 0, v[138:139]
	s_mov_b32 m0, s13
	s_nop 0
	global_load_lds_dwordx4 v[216:217], off
	s_mov_b32 m0, s14
	s_nop 0
	global_load_lds_dwordx4 v[218:219], off
	s_waitcnt vmcnt(8)
	s_waitcnt lgkmcnt(0)
	s_barrier
; #define PG8_STAGE(bufoff, gbase, voff) do { _Pragma("unroll") for (int _i = 0; _i < 2; ++_i) \
;         __builtin_amdgcn_global_load_lds((const unsigned*)((const char*)(gbase) + (voff)[_i]), (LAS unsigned*)(lds + (bufoff) + ldsw + _i * 8192), 16, 0, 0); } while (0)
; #define PG8_LDA(dst, b, h) do { _Pragma("unroll") for (int m = 0; m < 4; ++m) _Pragma("unroll") for (int k = 0; k < 2; ++k) dst[m][k] = *(const LAS bf16x8*)(lds + PG8_SA(b, h) + aoff + m * 2048 + k * 1024); } while (0)
; #define PG8_LDB(dst, b, h) do { _Pragma("unroll") for (int n = 0; n < 2; ++n) _Pragma("unroll") for (int k = 0; k < 2; ++k) dst[n][k] = *(const LAS bf16x8*)(lds + PG8_SB(b, h) + boff + n * 2048 + k * 1024); } while (0)
; #define PG8_MMA(ai, bj, At, Bt) do { __builtin_amdgcn_s_setprio(1); _Pragma("unroll") for (int m = 0; m < 4; ++m) _Pragma("unroll") for (int n = 0; n < 2; ++n) _Pragma("unroll") for (int k = 0; k < 2; ++k) \
;         acc[ai][bj][m][n] = __builtin_amdgcn_mfma_f32_16x16x32_bf16(Bt[n][k], At[m][k], acc[ai][bj][m][n], 0, 0, 0); __builtin_amdgcn_s_setprio(0); } while (0)
; #define PG8_WAIT_V(n) asm volatile("s_waitcnt vmcnt(" #n ")" ::: "memory")
; #define PG8_WAIT_L(n) asm volatile("s_waitcnt lgkmcnt(" #n ")" ::: "memory")
; #define PG8_BAR __builtin_amdgcn_s_barrier()
; #define PG8_SCHED __builtin_amdgcn_sched_barrier(0)
; template <class Epi>
; __device__ __forceinline__ void gemm_phase(LAS unsigned char* lds, const Gemm g, const StaticOrder& S, const Epi& E) {
;     ...
;             PG8_WAIT_V(8); PG8_WAIT_L(0); PG8_BAR; PG8_MMA(1, 0, At, B0); PG8_MMA(1, 1, At, B1); PG8_BAR; PG8_SCHED;
;             PG8_LDB(B0, 1, 0); PG8_LDB(B1, 1, 1); PG8_SCHED; PG8_LDA(At, 1, 0); PG8_STAGE(PG8_SA(0, 1), a2 + hstepA, voffA);
;             PG8_WAIT_V(8); PG8_WAIT_L(0); PG8_BAR; PG8_MMA(0, 0, At, B0); PG8_MMA(0, 1, At, B1); PG8_BAR; PG8_SCHED;
	s_setprio 1
	s_waitcnt lgkmcnt(0)
	v_mfma_f32_16x16x32_bf16 v[94:97], v[130:133], v[182:185], v[94:97]
	v_mfma_f32_16x16x32_bf16 v[90:93], v[150:153], v[182:185], v[90:93]
	v_mfma_f32_16x16x32_bf16 v[86:89], v[130:133], v[190:193], v[86:89]
	v_mfma_f32_16x16x32_bf16 v[82:85], v[150:153], v[190:193], v[82:85]
	v_mfma_f32_16x16x32_bf16 v[78:81], v[130:133], v[198:201], v[78:81]
	v_mfma_f32_16x16x32_bf16 v[74:77], v[150:153], v[198:201], v[74:77]
	v_mfma_f32_16x16x32_bf16 v[70:73], v[130:133], v[206:209], v[70:73]
	v_mfma_f32_16x16x32_bf16 v[66:69], v[150:153], v[206:209], v[66:69]
	v_mfma_f32_16x16x32_bf16 v[94:97], v[134:137], v[186:189], v[94:97]
	v_mfma_f32_16x16x32_bf16 v[90:93], v[158:161], v[186:189], v[90:93]
	v_mfma_f32_16x16x32_bf16 v[86:89], v[134:137], v[194:197], v[86:89]
	v_mfma_f32_16x16x32_bf16 v[82:85], v[158:161], v[194:197], v[82:85]
	v_mfma_f32_16x16x32_bf16 v[78:81], v[134:137], v[202:205], v[78:81]
	v_mfma_f32_16x16x32_bf16 v[74:77], v[158:161], v[202:205], v[74:77]
	v_mfma_f32_16x16x32_bf16 v[70:73], v[134:137], v[210:213], v[70:73]
	v_mfma_f32_16x16x32_bf16 v[66:69], v[158:161], v[210:213], v[66:69]
	v_mfma_f32_16x16x32_bf16 v[30:33], v[162:165], v[182:185], v[30:33]
	v_mfma_f32_16x16x32_bf16 v[26:29], v[170:173], v[182:185], v[26:29]
	v_mfma_f32_16x16x32_bf16 v[22:25], v[162:165], v[190:193], v[22:25]
	v_mfma_f32_16x16x32_bf16 v[18:21], v[170:173], v[190:193], v[18:21]
	v_mfma_f32_16x16x32_bf16 v[14:17], v[162:165], v[198:201], v[14:17]
	v_mfma_f32_16x16x32_bf16 v[10:13], v[170:173], v[198:201], v[10:13]
	v_mfma_f32_16x16x32_bf16 v[6:9], v[162:165], v[206:209], v[6:9]
	v_mfma_f32_16x16x32_bf16 v[2:5], v[170:173], v[206:209], v[2:5]
	v_mfma_f32_16x16x32_bf16 v[30:33], v[166:169], v[186:189], v[30:33]
	v_mfma_f32_16x16x32_bf16 v[26:29], v[174:177], v[186:189], v[26:29]
	v_mfma_f32_16x16x32_bf16 v[22:25], v[166:169], v[194:197], v[22:25]
	v_mfma_f32_16x16x32_bf16 v[18:21], v[174:177], v[194:197], v[18:21]
	v_mfma_f32_16x16x32_bf16 v[14:17], v[166:169], v[202:205], v[14:17]
	v_mfma_f32_16x16x32_bf16 v[10:13], v[174:177], v[202:205], v[10:13]
	v_mfma_f32_16x16x32_bf16 v[6:9], v[166:169], v[210:213], v[6:9]
	v_mfma_f32_16x16x32_bf16 v[2:5], v[174:177], v[210:213], v[2:5]
	s_setprio 0
	s_barrier
	s_add_i32 s51, 0, 0x18000
	v_add_u32_e32 v0, s51, v156
	s_add_i32 s52, 0, 0x1c000
	ds_read_b128 v[130:133], v0
	ds_read_b128 v[134:137], v0 offset:1024
	ds_read_b128 v[150:153], v0 offset:2048
	ds_read_b128 v[158:161], v0 offset:3072
	v_add_u32_e32 v0, s52, v156
	ds_read_b128 v[162:165], v0
	ds_read_b128 v[166:169], v0 offset:1024
	ds_read_b128 v[170:173], v0 offset:2048
	ds_read_b128 v[174:177], v0 offset:3072
	s_add_u32 s40, s48, 0x40000
	s_addc_u32 s41, s49, 0
	s_mov_b32 m0, s15
	v_lshl_add_u64 v[220:221], s[40:41], 0, v[138:139]
	ds_read_b128 v[182:185], v157 offset:32768
	ds_read_b128 v[186:189], v157 offset:33792
	ds_read_b128 v[190:193], v157 offset:34816
	ds_read_b128 v[194:197], v157 offset:35840
	ds_read_b128 v[198:201], v157 offset:36864
	ds_read_b128 v[202:205], v157 offset:37888
	ds_read_b128 v[206:209], v157 offset:38912
	ds_read_b128 v[210:213], v157 offset:39936
	global_load_lds_dwordx4 v[220:221], off
	v_lshl_add_u64 v[220:221], s[40:41], 0, v[142:143]
	s_mov_b32 m0, s16
	s_nop 0
	global_load_lds_dwordx4 v[220:221], off
	s_waitcnt vmcnt(8)
	s_waitcnt lgkmcnt(0)
	s_barrier
	s_setprio 1
	s_waitcnt lgkmcnt(0)
	v_mfma_f32_16x16x32_bf16 v[126:129], v[130:133], v[182:185], v[126:129]
	v_mfma_f32_16x16x32_bf16 v[122:125], v[150:153], v[182:185], v[122:125]
	v_mfma_f32_16x16x32_bf16 v[118:121], v[130:133], v[190:193], v[118:121]
	v_mfma_f32_16x16x32_bf16 v[114:117], v[150:153], v[190:193], v[114:117]
	v_mfma_f32_16x16x32_bf16 v[110:113], v[130:133], v[198:201], v[110:113]
	v_mfma_f32_16x16x32_bf16 v[106:109], v[150:153], v[198:201], v[106:109]
	v_mfma_f32_16x16x32_bf16 v[102:105], v[130:133], v[206:209], v[102:105]
	v_mfma_f32_16x16x32_bf16 v[98:101], v[150:153], v[206:209], v[98:101]
	v_mfma_f32_16x16x32_bf16 v[126:129], v[134:137], v[186:189], v[126:129]
	v_mfma_f32_16x16x32_bf16 v[122:125], v[158:161], v[186:189], v[122:125]
	v_mfma_f32_16x16x32_bf16 v[118:121], v[134:137], v[194:197], v[118:121]
	v_mfma_f32_16x16x32_bf16 v[114:117], v[158:161], v[194:197], v[114:117]
	v_mfma_f32_16x16x32_bf16 v[110:113], v[134:137], v[202:205], v[110:113]
	v_mfma_f32_16x16x32_bf16 v[106:109], v[158:161], v[202:205], v[106:109]
	v_mfma_f32_16x16x32_bf16 v[102:105], v[134:137], v[210:213], v[102:105]
	v_mfma_f32_16x16x32_bf16 v[98:101], v[158:161], v[210:213], v[98:101]
	v_mfma_f32_16x16x32_bf16 v[62:65], v[162:165], v[182:185], v[62:65]
	v_mfma_f32_16x16x32_bf16 v[58:61], v[170:173], v[182:185], v[58:61]
	v_mfma_f32_16x16x32_bf16 v[54:57], v[162:165], v[190:193], v[54:57]
	v_mfma_f32_16x16x32_bf16 v[50:53], v[170:173], v[190:193], v[50:53]
	v_mfma_f32_16x16x32_bf16 v[46:49], v[162:165], v[198:201], v[46:49]
	v_mfma_f32_16x16x32_bf16 v[42:45], v[170:173], v[198:201], v[42:45]
	v_mfma_f32_16x16x32_bf16 v[38:41], v[162:165], v[206:209], v[38:41]
	v_mfma_f32_16x16x32_bf16 v[34:37], v[170:173], v[206:209], v[34:37]
	v_mfma_f32_16x16x32_bf16 v[62:65], v[166:169], v[186:189], v[62:65]
	v_mfma_f32_16x16x32_bf16 v[58:61], v[174:177], v[186:189], v[58:61]
	v_mfma_f32_16x16x32_bf16 v[54:57], v[166:169], v[194:197], v[54:57]
	v_mfma_f32_16x16x32_bf16 v[50:53], v[174:177], v[194:197], v[50:53]
	v_mfma_f32_16x16x32_bf16 v[46:49], v[166:169], v[202:205], v[46:49]
	v_mfma_f32_16x16x32_bf16 v[42:45], v[174:177], v[202:205], v[42:45]
	v_mfma_f32_16x16x32_bf16 v[38:41], v[166:169], v[210:213], v[38:41]
	v_mfma_f32_16x16x32_bf16 v[34:37], v[174:177], v[210:213], v[34:37]
	s_setprio 0
	s_barrier
; #define PG8_STAGE(bufoff, gbase, voff) do { _Pragma("unroll") for (int _i = 0; _i < 2; ++_i) \
;         __builtin_amdgcn_global_load_lds((const unsigned*)((const char*)(gbase) + (voff)[_i]), (LAS unsigned*)(lds + (bufoff) + ldsw + _i * 8192), 16, 0, 0); } while (0)
; #define PG8_LDA(dst, b, h) do { _Pragma("unroll") for (int m = 0; m < 4; ++m) _Pragma("unroll") for (int k = 0; k < 2; ++k) dst[m][k] = *(const LAS bf16x8*)(lds + PG8_SA(b, h) + aoff + m * 2048 + k * 1024); } while (0)
; #define PG8_MMA(ai, bj, At, Bt) do { __builtin_amdgcn_s_setprio(1); _Pragma("unroll") for (int m = 0; m < 4; ++m) _Pragma("unroll") for (int n = 0; n < 2; ++n) _Pragma("unroll") for (int k = 0; k < 2; ++k) \
;         acc[ai][bj][m][n] = __builtin_amdgcn_mfma_f32_16x16x32_bf16(Bt[n][k], At[m][k], acc[ai][bj][m][n], 0, 0, 0); __builtin_amdgcn_s_setprio(0); } while (0)
; #define PG8_WAIT_V(n) asm volatile("s_waitcnt vmcnt(" #n ")" ::: "memory")
; #define PG8_WAIT_L(n) asm volatile("s_waitcnt lgkmcnt(" #n ")" ::: "memory")
; #define PG8_BAR __builtin_amdgcn_s_barrier()
; #define PG8_SCHED __builtin_amdgcn_sched_barrier(0)
; template <class Epi>
; __device__ __forceinline__ void gemm_phase(LAS unsigned char* lds, const Gemm g, const StaticOrder& S, const Epi& E) {
;     ...
;             PG8_LDA(At, 1, 1); PG8_STAGE(PG8_SB(1, 0), b3, voffB); PG8_STAGE(PG8_SB(1, 1), b3 + hstepB, voffB); PG8_STAGE(PG8_SA(1, 0), a3, voffA);
;             PG8_WAIT_V(8); PG8_WAIT_L(0); PG8_BAR; PG8_MMA(1, 0, At, B0); PG8_MMA(1, 1, At, B1); PG8_BAR; PG8_SCHED;
;         }
;         if (wr == 0) PG8_BAR;
	s_add_i32 s40, s51, s12
	v_lshl_add_u64 v[178:179], v[178:179], 0, s[34:35]
	s_mov_b32 m0, s40
	ds_read_b128 v[182:185], v157 offset:49152
	ds_read_b128 v[186:189], v157 offset:50176
	ds_read_b128 v[190:193], v157 offset:51200
	ds_read_b128 v[194:197], v157 offset:52224
	ds_read_b128 v[198:201], v157 offset:53248
	ds_read_b128 v[202:205], v157 offset:54272
	ds_read_b128 v[206:209], v157 offset:55296
	ds_read_b128 v[210:213], v157 offset:56320
	global_load_lds_dwordx4 v[178:179], off
	s_add_i32 m0, s40, 0x2000
	s_add_u32 s40, s44, 0x40080
	v_lshl_add_u64 v[178:179], v[214:215], 0, s[34:35]
	s_addc_u32 s41, s45, 0
	s_add_i32 s44, s52, s12
	global_load_lds_dwordx4 v[178:179], off
	v_lshl_add_u64 v[178:179], s[40:41], 0, v[140:141]
	s_mov_b32 m0, s44
	s_nop 0
	global_load_lds_dwordx4 v[178:179], off
	v_lshl_add_u64 v[178:179], s[40:41], 0, v[144:145]
	s_add_i32 m0, s44, 0x2000
	s_nop 0
	global_load_lds_dwordx4 v[178:179], off
	v_lshl_add_u64 v[178:179], v[216:217], 0, s[34:35]
	s_mov_b32 m0, s18
	s_nop 0
	global_load_lds_dwordx4 v[178:179], off
	v_lshl_add_u64 v[178:179], v[218:219], 0, s[34:35]
	s_mov_b32 m0, s19
	s_nop 0
	global_load_lds_dwordx4 v[178:179], off
	s_waitcnt vmcnt(8)
	s_waitcnt lgkmcnt(0)
	s_barrier
	s_setprio 1
	s_waitcnt lgkmcnt(0)
	v_mfma_f32_16x16x32_bf16 v[94:97], v[130:133], v[182:185], v[94:97]
	v_mfma_f32_16x16x32_bf16 v[90:93], v[150:153], v[182:185], v[90:93]
	v_mfma_f32_16x16x32_bf16 v[86:89], v[130:133], v[190:193], v[86:89]
	v_mfma_f32_16x16x32_bf16 v[82:85], v[150:153], v[190:193], v[82:85]
	v_mfma_f32_16x16x32_bf16 v[78:81], v[130:133], v[198:201], v[78:81]
	v_mfma_f32_16x16x32_bf16 v[74:77], v[150:153], v[198:201], v[74:77]
	v_mfma_f32_16x16x32_bf16 v[70:73], v[130:133], v[206:209], v[70:73]
	v_mfma_f32_16x16x32_bf16 v[66:69], v[150:153], v[206:209], v[66:69]
	v_mfma_f32_16x16x32_bf16 v[94:97], v[134:137], v[186:189], v[94:97]
	v_mfma_f32_16x16x32_bf16 v[90:93], v[158:161], v[186:189], v[90:93]
	v_mfma_f32_16x16x32_bf16 v[86:89], v[134:137], v[194:197], v[86:89]
	v_mfma_f32_16x16x32_bf16 v[82:85], v[158:161], v[194:197], v[82:85]
	v_mfma_f32_16x16x32_bf16 v[78:81], v[134:137], v[202:205], v[78:81]
	v_mfma_f32_16x16x32_bf16 v[74:77], v[158:161], v[202:205], v[74:77]
	v_mfma_f32_16x16x32_bf16 v[70:73], v[134:137], v[210:213], v[70:73]
	v_mfma_f32_16x16x32_bf16 v[66:69], v[158:161], v[210:213], v[66:69]
	v_mfma_f32_16x16x32_bf16 v[30:33], v[162:165], v[182:185], v[30:33]
	v_mfma_f32_16x16x32_bf16 v[26:29], v[170:173], v[182:185], v[26:29]
	v_mfma_f32_16x16x32_bf16 v[22:25], v[162:165], v[190:193], v[22:25]
	v_mfma_f32_16x16x32_bf16 v[18:21], v[170:173], v[190:193], v[18:21]
	v_mfma_f32_16x16x32_bf16 v[14:17], v[162:165], v[198:201], v[14:17]
	v_mfma_f32_16x16x32_bf16 v[10:13], v[170:173], v[198:201], v[10:13]
	v_mfma_f32_16x16x32_bf16 v[6:9], v[162:165], v[206:209], v[6:9]
	v_mfma_f32_16x16x32_bf16 v[2:5], v[170:173], v[206:209], v[2:5]
	v_mfma_f32_16x16x32_bf16 v[30:33], v[166:169], v[186:189], v[30:33]
	v_mfma_f32_16x16x32_bf16 v[26:29], v[174:177], v[186:189], v[26:29]
	v_mfma_f32_16x16x32_bf16 v[22:25], v[166:169], v[194:197], v[22:25]
	v_mfma_f32_16x16x32_bf16 v[18:21], v[174:177], v[194:197], v[18:21]
	v_mfma_f32_16x16x32_bf16 v[14:17], v[166:169], v[202:205], v[14:17]
	v_mfma_f32_16x16x32_bf16 v[10:13], v[174:177], v[202:205], v[10:13]
	v_mfma_f32_16x16x32_bf16 v[6:9], v[166:169], v[210:213], v[6:9]
	v_mfma_f32_16x16x32_bf16 v[2:5], v[174:177], v[210:213], v[2:5]
	s_setprio 0
	s_barrier
	s_add_i32 s50, s50, 2
	s_add_u32 s31, s31, 0x100
	s_addc_u32 s46, s46, 0
	s_cmp_gt_u32 s50, 13
	s_mov_b64 s[40:41], s[42:43]
	s_cbranch_scc0 .LBB0_355
	s_and_b64 vcc, exec, s[82:83]
	s_cbranch_vccz .LBB0_358
	s_barrier

; #define PG8_STAGE(bufoff, gbase, voff) do { _Pragma("unroll") for (int _i = 0; _i < 2; ++_i) \
;         __builtin_amdgcn_global_load_lds((const unsigned*)((const char*)(gbase) + (voff)[_i]), (LAS unsigned*)(lds + (bufoff) + ldsw + _i * 8192), 16, 0, 0); } while (0)
; #define PG8_LDA(dst, b, h) do { _Pragma("unroll") for (int m = 0; m < 4; ++m) _Pragma("unroll") for (int k = 0; k < 2; ++k) dst[m][k] = *(const LAS bf16x8*)(lds + PG8_SA(b, h) + aoff + m * 2048 + k * 1024); } while (0)
; #define PG8_LDB(dst, b, h) do { _Pragma("unroll") for (int n = 0; n < 2; ++n) _Pragma("unroll") for (int k = 0; k < 2; ++k) dst[n][k] = *(const LAS bf16x8*)(lds + PG8_SB(b, h) + boff + n * 2048 + k * 1024); } while (0)
; #define PG8_MMA(ai, bj, At, Bt) do { __builtin_amdgcn_s_setprio(1); _Pragma("unroll") for (int m = 0; m < 4; ++m) _Pragma("unroll") for (int n = 0; n < 2; ++n) _Pragma("unroll") for (int k = 0; k < 2; ++k) \
;         acc[ai][bj][m][n] = __builtin_amdgcn_mfma_f32_16x16x32_bf16(Bt[n][k], At[m][k], acc[ai][bj][m][n], 0, 0, 0); __builtin_amdgcn_s_setprio(0); } while (0)
; #define PG8_WAIT_V(n) asm volatile("s_waitcnt vmcnt(" #n ")" ::: "memory")
; #define PG8_WAIT_L(n) asm volatile("s_waitcnt lgkmcnt(" #n ")" ::: "memory")
; #define PG8_BAR __builtin_amdgcn_s_barrier()
; #define PG8_SCHED __builtin_amdgcn_sched_barrier(0)
; template <class Epi>
; __device__ __forceinline__ void gemm_phase(LAS unsigned char* lds, const Gemm g, const StaticOrder& S, const Epi& E) {
;     ...
;             PG8_LDB(B0, 0, 0); PG8_LDB(B1, 0, 1); PG8_SCHED; PG8_LDA(At, 0, 0); PG8_STAGE(PG8_SA(1, 1), a1 + hstepA, voffA);
;             PG8_WAIT_V(8); PG8_WAIT_L(0); PG8_BAR; PG8_MMA(0, 0, At, B0); PG8_MMA(0, 1, At, B1); PG8_BAR; PG8_SCHED;
;             PG8_LDA(At, 0, 1); PG8_STAGE(PG8_SB(0, 0), b2, voffB); PG8_STAGE(PG8_SB(0, 1), b2 + hstepB, voffB); PG8_STAGE(PG8_SA(0, 0), a2, voffA);
;             PG8_WAIT_V(8); PG8_WAIT_L(0); PG8_BAR; PG8_MMA(1, 0, At, B0); PG8_MMA(1, 1, At, B1); PG8_BAR; PG8_SCHED;
.LBB0_729:
	s_add_u32 s0, s4, s6
	s_addc_u32 s1, s5, s7
	s_add_u32 s0, s0, 0x100
	s_addc_u32 s1, s1, 0
	s_add_u32 s48, s54, s6
	s_addc_u32 s49, s55, s7
	s_add_i32 s50, 0, 0x10000
	s_cmpk_eq_i32 s6, 0x700
	s_cselect_b32 s9, s27, s1
	s_cselect_b32 s8, s31, s0
	v_add_u32_e32 v144, s50, v149
	s_cselect_b32 s1, s45, s49
	s_cselect_b32 s0, s52, s48
	s_add_i32 s51, 0, 0x14000
	ds_read_b128 v[152:155], v144
	ds_read_b128 v[156:159], v144 offset:1024
	ds_read_b128 v[160:163], v144 offset:2048
	ds_read_b128 v[164:167], v144 offset:3072
	v_add_u32_e32 v144, s51, v149
	ds_read_b128 v[168:171], v144
	ds_read_b128 v[172:175], v144 offset:1024
	ds_read_b128 v[176:179], v144 offset:2048
	ds_read_b128 v[182:185], v144 offset:3072
	v_lshl_add_u64 v[144:145], v[142:143], 0, s[6:7]
	s_add_i32 m0, s15, 0xc000
	ds_read_b128 v[186:189], v150
	ds_read_b128 v[190:193], v150 offset:1024
	ds_read_b128 v[194:197], v150 offset:2048
	ds_read_b128 v[198:201], v150 offset:3072
	ds_read_b128 v[202:205], v150 offset:4096
	ds_read_b128 v[206:209], v150 offset:5120
	ds_read_b128 v[210:213], v150 offset:6144
	ds_read_b128 v[214:217], v150 offset:7168
	global_load_lds_dwordx4 v[144:145], off
	v_lshl_add_u64 v[144:145], v[140:141], 0, s[6:7]
	s_add_i32 m0, s15, 0xe000
	s_nop 0
	global_load_lds_dwordx4 v[144:145], off
	s_waitcnt vmcnt(8)
	s_waitcnt lgkmcnt(0)
	s_barrier
	s_setprio 1
	s_waitcnt lgkmcnt(0)
	v_mfma_f32_16x16x32_bf16 v[126:129], v[152:155], v[186:189], v[126:129]
	v_mfma_f32_16x16x32_bf16 v[82:85], v[160:163], v[186:189], v[82:85]
	v_mfma_f32_16x16x32_bf16 v[122:125], v[152:155], v[194:197], v[122:125]
	v_mfma_f32_16x16x32_bf16 v[86:89], v[160:163], v[194:197], v[86:89]
	v_mfma_f32_16x16x32_bf16 v[118:121], v[152:155], v[202:205], v[118:121]
	v_mfma_f32_16x16x32_bf16 v[90:93], v[160:163], v[202:205], v[90:93]
	v_mfma_f32_16x16x32_bf16 v[114:117], v[152:155], v[210:213], v[114:117]
	v_mfma_f32_16x16x32_bf16 v[94:97], v[160:163], v[210:213], v[94:97]
	v_mfma_f32_16x16x32_bf16 v[126:129], v[156:159], v[190:193], v[126:129]
	v_mfma_f32_16x16x32_bf16 v[82:85], v[164:167], v[190:193], v[82:85]
	v_mfma_f32_16x16x32_bf16 v[122:125], v[156:159], v[198:201], v[122:125]
	v_mfma_f32_16x16x32_bf16 v[86:89], v[164:167], v[198:201], v[86:89]
	v_mfma_f32_16x16x32_bf16 v[118:121], v[156:159], v[206:209], v[118:121]
	v_mfma_f32_16x16x32_bf16 v[90:93], v[164:167], v[206:209], v[90:93]
	v_mfma_f32_16x16x32_bf16 v[114:117], v[156:159], v[214:217], v[114:117]
	v_mfma_f32_16x16x32_bf16 v[94:97], v[164:167], v[214:217], v[94:97]
	v_mfma_f32_16x16x32_bf16 v[110:113], v[168:171], v[186:189], v[110:113]
	v_mfma_f32_16x16x32_bf16 v[66:69], v[176:179], v[186:189], v[66:69]
	v_mfma_f32_16x16x32_bf16 v[106:109], v[168:171], v[194:197], v[106:109]
	v_mfma_f32_16x16x32_bf16 v[70:73], v[176:179], v[194:197], v[70:73]
	v_mfma_f32_16x16x32_bf16 v[102:105], v[168:171], v[202:205], v[102:105]
	v_mfma_f32_16x16x32_bf16 v[74:77], v[176:179], v[202:205], v[74:77]
	v_mfma_f32_16x16x32_bf16 v[98:101], v[168:171], v[210:213], v[98:101]
	v_mfma_f32_16x16x32_bf16 v[78:81], v[176:179], v[210:213], v[78:81]
	v_mfma_f32_16x16x32_bf16 v[110:113], v[172:175], v[190:193], v[110:113]
	v_mfma_f32_16x16x32_bf16 v[66:69], v[182:185], v[190:193], v[66:69]
	v_mfma_f32_16x16x32_bf16 v[106:109], v[172:175], v[198:201], v[106:109]
	v_mfma_f32_16x16x32_bf16 v[70:73], v[182:185], v[198:201], v[70:73]
	v_mfma_f32_16x16x32_bf16 v[102:105], v[172:175], v[206:209], v[102:105]
	v_mfma_f32_16x16x32_bf16 v[74:77], v[182:185], v[206:209], v[74:77]
	v_mfma_f32_16x16x32_bf16 v[98:101], v[172:175], v[214:217], v[98:101]
	v_mfma_f32_16x16x32_bf16 v[78:81], v[182:185], v[214:217], v[78:81]
	s_setprio 0
	s_barrier
	s_add_i32 s48, s50, s14
	v_lshl_add_u64 v[144:145], s[0:1], 0, v[0:1]
	s_mov_b32 m0, s48
	ds_read_b128 v[186:189], v150 offset:16384
	ds_read_b128 v[190:193], v150 offset:17408
	ds_read_b128 v[194:197], v150 offset:18432
	ds_read_b128 v[198:201], v150 offset:19456
	ds_read_b128 v[202:205], v150 offset:20480
	ds_read_b128 v[206:209], v150 offset:21504
	ds_read_b128 v[210:213], v150 offset:22528
	ds_read_b128 v[214:217], v150 offset:23552
	global_load_lds_dwordx4 v[144:145], off
	s_add_i32 m0, s48, 0x2000
	s_add_u32 s48, s0, 0x40000
	v_lshl_add_u64 v[218:219], s[0:1], 0, v[134:135]
	s_addc_u32 s49, s1, 0
	s_add_i32 s50, s51, s14
	global_load_lds_dwordx4 v[218:219], off
	v_lshl_add_u64 v[220:221], s[48:49], 0, v[0:1]
	s_mov_b32 m0, s50
	v_lshl_add_u64 v[222:223], s[8:9], 0, v[132:133]
	global_load_lds_dwordx4 v[220:221], off
	v_lshl_add_u64 v[220:221], s[48:49], 0, v[134:135]
	s_add_i32 m0, s50, 0x2000
	s_nop 0
	global_load_lds_dwordx4 v[220:221], off
	v_lshl_add_u64 v[220:221], s[8:9], 0, v[130:131]
	s_mov_b32 m0, s15
	s_nop 0
	global_load_lds_dwordx4 v[220:221], off
	s_mov_b32 m0, s16
	s_nop 0
	global_load_lds_dwordx4 v[222:223], off
	s_waitcnt vmcnt(8)
	s_waitcnt lgkmcnt(0)
	s_barrier
; #define PG8_STAGE(bufoff, gbase, voff) do { _Pragma("unroll") for (int _i = 0; _i < 2; ++_i) \
;         __builtin_amdgcn_global_load_lds((const unsigned*)((const char*)(gbase) + (voff)[_i]), (LAS unsigned*)(lds + (bufoff) + ldsw + _i * 8192), 16, 0, 0); } while (0)
; #define PG8_LDA(dst, b, h) do { _Pragma("unroll") for (int m = 0; m < 4; ++m) _Pragma("unroll") for (int k = 0; k < 2; ++k) dst[m][k] = *(const LAS bf16x8*)(lds + PG8_SA(b, h) + aoff + m * 2048 + k * 1024); } while (0)
; #define PG8_LDB(dst, b, h) do { _Pragma("unroll") for (int n = 0; n < 2; ++n) _Pragma("unroll") for (int k = 0; k < 2; ++k) dst[n][k] = *(const LAS bf16x8*)(lds + PG8_SB(b, h) + boff + n * 2048 + k * 1024); } while (0)
; #define PG8_MMA(ai, bj, At, Bt) do { __builtin_amdgcn_s_setprio(1); _Pragma("unroll") for (int m = 0; m < 4; ++m) _Pragma("unroll") for (int n = 0; n < 2; ++n) _Pragma("unroll") for (int k = 0; k < 2; ++k) \
;         acc[ai][bj][m][n] = __builtin_amdgcn_mfma_f32_16x16x32_bf16(Bt[n][k], At[m][k], acc[ai][bj][m][n], 0, 0, 0); __builtin_amdgcn_s_setprio(0); } while (0)
; #define PG8_WAIT_V(n) asm volatile("s_waitcnt vmcnt(" #n ")" ::: "memory")
; #define PG8_WAIT_L(n) asm volatile("s_waitcnt lgkmcnt(" #n ")" ::: "memory")
; #define PG8_BAR __builtin_amdgcn_s_barrier()
; #define PG8_SCHED __builtin_amdgcn_sched_barrier(0)
; template <class Epi>
; __device__ __forceinline__ void gemm_phase(LAS unsigned char* lds, const Gemm g, const StaticOrder& S, const Epi& E) {
;     ...
;             PG8_WAIT_V(8); PG8_WAIT_L(0); PG8_BAR; PG8_MMA(1, 0, At, B0); PG8_MMA(1, 1, At, B1); PG8_BAR; PG8_SCHED;
;             PG8_LDB(B0, 1, 0); PG8_LDB(B1, 1, 1); PG8_SCHED; PG8_LDA(At, 1, 0); PG8_STAGE(PG8_SA(0, 1), a2 + hstepA, voffA);
;             PG8_WAIT_V(8); PG8_WAIT_L(0); PG8_BAR; PG8_MMA(0, 0, At, B0); PG8_MMA(0, 1, At, B1); PG8_BAR; PG8_SCHED;
	s_setprio 1
	s_waitcnt lgkmcnt(0)
	v_mfma_f32_16x16x32_bf16 v[62:65], v[152:155], v[186:189], v[62:65]
	v_mfma_f32_16x16x32_bf16 v[18:21], v[160:163], v[186:189], v[18:21]
	v_mfma_f32_16x16x32_bf16 v[58:61], v[152:155], v[194:197], v[58:61]
	v_mfma_f32_16x16x32_bf16 v[22:25], v[160:163], v[194:197], v[22:25]
	v_mfma_f32_16x16x32_bf16 v[54:57], v[152:155], v[202:205], v[54:57]
	v_mfma_f32_16x16x32_bf16 v[26:29], v[160:163], v[202:205], v[26:29]
	v_mfma_f32_16x16x32_bf16 v[50:53], v[152:155], v[210:213], v[50:53]
	v_mfma_f32_16x16x32_bf16 v[30:33], v[160:163], v[210:213], v[30:33]
	v_mfma_f32_16x16x32_bf16 v[62:65], v[156:159], v[190:193], v[62:65]
	v_mfma_f32_16x16x32_bf16 v[18:21], v[164:167], v[190:193], v[18:21]
	v_mfma_f32_16x16x32_bf16 v[58:61], v[156:159], v[198:201], v[58:61]
	v_mfma_f32_16x16x32_bf16 v[22:25], v[164:167], v[198:201], v[22:25]
	v_mfma_f32_16x16x32_bf16 v[54:57], v[156:159], v[206:209], v[54:57]
	v_mfma_f32_16x16x32_bf16 v[26:29], v[164:167], v[206:209], v[26:29]
	v_mfma_f32_16x16x32_bf16 v[50:53], v[156:159], v[214:217], v[50:53]
	v_mfma_f32_16x16x32_bf16 v[30:33], v[164:167], v[214:217], v[30:33]
	v_mfma_f32_16x16x32_bf16 v[46:49], v[168:171], v[186:189], v[46:49]
	v_mfma_f32_16x16x32_bf16 v[2:5], v[176:179], v[186:189], v[2:5]
	v_mfma_f32_16x16x32_bf16 v[42:45], v[168:171], v[194:197], v[42:45]
	v_mfma_f32_16x16x32_bf16 v[6:9], v[176:179], v[194:197], v[6:9]
	v_mfma_f32_16x16x32_bf16 v[38:41], v[168:171], v[202:205], v[38:41]
	v_mfma_f32_16x16x32_bf16 v[10:13], v[176:179], v[202:205], v[10:13]
	v_mfma_f32_16x16x32_bf16 v[34:37], v[168:171], v[210:213], v[34:37]
	v_mfma_f32_16x16x32_bf16 v[14:17], v[176:179], v[210:213], v[14:17]
	v_mfma_f32_16x16x32_bf16 v[46:49], v[172:175], v[190:193], v[46:49]
	v_mfma_f32_16x16x32_bf16 v[2:5], v[182:185], v[190:193], v[2:5]
	v_mfma_f32_16x16x32_bf16 v[42:45], v[172:175], v[198:201], v[42:45]
	v_mfma_f32_16x16x32_bf16 v[6:9], v[182:185], v[198:201], v[6:9]
	v_mfma_f32_16x16x32_bf16 v[38:41], v[172:175], v[206:209], v[38:41]
	v_mfma_f32_16x16x32_bf16 v[10:13], v[182:185], v[206:209], v[10:13]
	v_mfma_f32_16x16x32_bf16 v[34:37], v[172:175], v[214:217], v[34:37]
	v_mfma_f32_16x16x32_bf16 v[14:17], v[182:185], v[214:217], v[14:17]
	s_setprio 0
	s_barrier
	s_add_i32 s48, 0, 0x18000
	v_add_u32_e32 v151, s48, v149
	s_add_i32 s49, 0, 0x1c000
	ds_read_b128 v[152:155], v151
	ds_read_b128 v[156:159], v151 offset:1024
	ds_read_b128 v[160:163], v151 offset:2048
	ds_read_b128 v[164:167], v151 offset:3072
	v_add_u32_e32 v151, s49, v149
	ds_read_b128 v[168:171], v151
	ds_read_b128 v[172:175], v151 offset:1024
	ds_read_b128 v[176:179], v151 offset:2048
	ds_read_b128 v[182:185], v151 offset:3072
	s_add_u32 s8, s8, 0x40000
	s_addc_u32 s9, s9, 0
	s_mov_b32 m0, s17
	v_lshl_add_u64 v[224:225], s[8:9], 0, v[130:131]
	ds_read_b128 v[186:189], v150 offset:32768
	ds_read_b128 v[190:193], v150 offset:33792
	ds_read_b128 v[194:197], v150 offset:34816
	ds_read_b128 v[198:201], v150 offset:35840
	ds_read_b128 v[202:205], v150 offset:36864
	ds_read_b128 v[206:209], v150 offset:37888
	ds_read_b128 v[210:213], v150 offset:38912
	ds_read_b128 v[214:217], v150 offset:39936
	global_load_lds_dwordx4 v[224:225], off
	v_lshl_add_u64 v[224:225], s[8:9], 0, v[132:133]
	s_mov_b32 m0, s18
	s_nop 0
	global_load_lds_dwordx4 v[224:225], off
	s_waitcnt vmcnt(8)
	s_waitcnt lgkmcnt(0)
	s_barrier
	s_setprio 1
	s_waitcnt lgkmcnt(0)
	v_mfma_f32_16x16x32_bf16 v[126:129], v[152:155], v[186:189], v[126:129]
	v_mfma_f32_16x16x32_bf16 v[82:85], v[160:163], v[186:189], v[82:85]
	v_mfma_f32_16x16x32_bf16 v[122:125], v[152:155], v[194:197], v[122:125]
	v_mfma_f32_16x16x32_bf16 v[86:89], v[160:163], v[194:197], v[86:89]
	v_mfma_f32_16x16x32_bf16 v[118:121], v[152:155], v[202:205], v[118:121]
	v_mfma_f32_16x16x32_bf16 v[90:93], v[160:163], v[202:205], v[90:93]
	v_mfma_f32_16x16x32_bf16 v[114:117], v[152:155], v[210:213], v[114:117]
	v_mfma_f32_16x16x32_bf16 v[94:97], v[160:163], v[210:213], v[94:97]
	v_mfma_f32_16x16x32_bf16 v[126:129], v[156:159], v[190:193], v[126:129]
	v_mfma_f32_16x16x32_bf16 v[82:85], v[164:167], v[190:193], v[82:85]
	v_mfma_f32_16x16x32_bf16 v[122:125], v[156:159], v[198:201], v[122:125]
	v_mfma_f32_16x16x32_bf16 v[86:89], v[164:167], v[198:201], v[86:89]
	v_mfma_f32_16x16x32_bf16 v[118:121], v[156:159], v[206:209], v[118:121]
	v_mfma_f32_16x16x32_bf16 v[90:93], v[164:167], v[206:209], v[90:93]
	v_mfma_f32_16x16x32_bf16 v[114:117], v[156:159], v[214:217], v[114:117]
	v_mfma_f32_16x16x32_bf16 v[94:97], v[164:167], v[214:217], v[94:97]
	v_mfma_f32_16x16x32_bf16 v[110:113], v[168:171], v[186:189], v[110:113]
	v_mfma_f32_16x16x32_bf16 v[66:69], v[176:179], v[186:189], v[66:69]
	v_mfma_f32_16x16x32_bf16 v[106:109], v[168:171], v[194:197], v[106:109]
	v_mfma_f32_16x16x32_bf16 v[70:73], v[176:179], v[194:197], v[70:73]
	v_mfma_f32_16x16x32_bf16 v[102:105], v[168:171], v[202:205], v[102:105]
	v_mfma_f32_16x16x32_bf16 v[74:77], v[176:179], v[202:205], v[74:77]
	v_mfma_f32_16x16x32_bf16 v[98:101], v[168:171], v[210:213], v[98:101]
	v_mfma_f32_16x16x32_bf16 v[78:81], v[176:179], v[210:213], v[78:81]
	v_mfma_f32_16x16x32_bf16 v[110:113], v[172:175], v[190:193], v[110:113]
	v_mfma_f32_16x16x32_bf16 v[66:69], v[182:185], v[190:193], v[66:69]
	v_mfma_f32_16x16x32_bf16 v[106:109], v[172:175], v[198:201], v[106:109]
	v_mfma_f32_16x16x32_bf16 v[70:73], v[182:185], v[198:201], v[70:73]
	v_mfma_f32_16x16x32_bf16 v[102:105], v[172:175], v[206:209], v[102:105]
	v_mfma_f32_16x16x32_bf16 v[74:77], v[182:185], v[206:209], v[74:77]
	v_mfma_f32_16x16x32_bf16 v[98:101], v[172:175], v[214:217], v[98:101]
	v_mfma_f32_16x16x32_bf16 v[78:81], v[182:185], v[214:217], v[78:81]
	s_setprio 0
	s_barrier
; #define PG8_STAGE(bufoff, gbase, voff) do { _Pragma("unroll") for (int _i = 0; _i < 2; ++_i) \
;         __builtin_amdgcn_global_load_lds((const unsigned*)((const char*)(gbase) + (voff)[_i]), (LAS unsigned*)(lds + (bufoff) + ldsw + _i * 8192), 16, 0, 0); } while (0)
; #define PG8_LDA(dst, b, h) do { _Pragma("unroll") for (int m = 0; m < 4; ++m) _Pragma("unroll") for (int k = 0; k < 2; ++k) dst[m][k] = *(const LAS bf16x8*)(lds + PG8_SA(b, h) + aoff + m * 2048 + k * 1024); } while (0)
; #define PG8_MMA(ai, bj, At, Bt) do { __builtin_amdgcn_s_setprio(1); _Pragma("unroll") for (int m = 0; m < 4; ++m) _Pragma("unroll") for (int n = 0; n < 2; ++n) _Pragma("unroll") for (int k = 0; k < 2; ++k) \
;         acc[ai][bj][m][n] = __builtin_amdgcn_mfma_f32_16x16x32_bf16(Bt[n][k], At[m][k], acc[ai][bj][m][n], 0, 0, 0); __builtin_amdgcn_s_setprio(0); } while (0)
; #define PG8_WAIT_V(n) asm volatile("s_waitcnt vmcnt(" #n ")" ::: "memory")
; #define PG8_WAIT_L(n) asm volatile("s_waitcnt lgkmcnt(" #n ")" ::: "memory")
; #define PG8_BAR __builtin_amdgcn_s_barrier()
; #define PG8_SCHED __builtin_amdgcn_sched_barrier(0)
; template <class Epi>
; __device__ __forceinline__ void gemm_phase(LAS unsigned char* lds, const Gemm g, const StaticOrder& S, const Epi& E) {
;     ...
;             PG8_LDA(At, 1, 1); PG8_STAGE(PG8_SB(1, 0), b3, voffB); PG8_STAGE(PG8_SB(1, 1), b3 + hstepB, voffB); PG8_STAGE(PG8_SA(1, 0), a3, voffA);
;             PG8_WAIT_V(8); PG8_WAIT_L(0); PG8_BAR; PG8_MMA(1, 0, At, B0); PG8_MMA(1, 1, At, B1); PG8_BAR; PG8_SCHED;
;         }
;         if (wr == 0) PG8_BAR;
	s_add_i32 s8, s48, s14
	v_lshl_add_u64 v[144:145], v[144:145], 0, s[34:35]
	s_mov_b32 m0, s8
	ds_read_b128 v[186:189], v150 offset:49152
	ds_read_b128 v[190:193], v150 offset:50176
	ds_read_b128 v[194:197], v150 offset:51200
	ds_read_b128 v[198:201], v150 offset:52224
	ds_read_b128 v[202:205], v150 offset:53248
	ds_read_b128 v[206:209], v150 offset:54272
	ds_read_b128 v[210:213], v150 offset:55296
	ds_read_b128 v[214:217], v150 offset:56320
	global_load_lds_dwordx4 v[144:145], off
	s_add_i32 m0, s8, 0x2000
	s_add_u32 s0, s0, 0x40080
	v_lshl_add_u64 v[144:145], v[218:219], 0, s[34:35]
	s_addc_u32 s1, s1, 0
	s_add_i32 s8, s49, s14
	global_load_lds_dwordx4 v[144:145], off
	v_lshl_add_u64 v[144:145], s[0:1], 0, v[0:1]
	s_mov_b32 m0, s8
	s_nop 0
	global_load_lds_dwordx4 v[144:145], off
	v_lshl_add_u64 v[144:145], s[0:1], 0, v[134:135]
	s_add_i32 m0, s8, 0x2000
	s_nop 0
	global_load_lds_dwordx4 v[144:145], off
	v_lshl_add_u64 v[144:145], v[220:221], 0, s[34:35]
	s_mov_b32 m0, s21
	s_nop 0
	global_load_lds_dwordx4 v[144:145], off
	v_lshl_add_u64 v[144:145], v[222:223], 0, s[34:35]
	s_mov_b32 m0, s22
	s_nop 0
	global_load_lds_dwordx4 v[144:145], off
	s_waitcnt vmcnt(8)
	s_waitcnt lgkmcnt(0)
	s_barrier
	s_setprio 1
	s_waitcnt lgkmcnt(0)
	v_mfma_f32_16x16x32_bf16 v[62:65], v[152:155], v[186:189], v[62:65]
	v_mfma_f32_16x16x32_bf16 v[18:21], v[160:163], v[186:189], v[18:21]
	v_mfma_f32_16x16x32_bf16 v[58:61], v[152:155], v[194:197], v[58:61]
	v_mfma_f32_16x16x32_bf16 v[22:25], v[160:163], v[194:197], v[22:25]
	v_mfma_f32_16x16x32_bf16 v[54:57], v[152:155], v[202:205], v[54:57]
	v_mfma_f32_16x16x32_bf16 v[26:29], v[160:163], v[202:205], v[26:29]
	v_mfma_f32_16x16x32_bf16 v[50:53], v[152:155], v[210:213], v[50:53]
	v_mfma_f32_16x16x32_bf16 v[30:33], v[160:163], v[210:213], v[30:33]
	v_mfma_f32_16x16x32_bf16 v[62:65], v[156:159], v[190:193], v[62:65]
	v_mfma_f32_16x16x32_bf16 v[18:21], v[164:167], v[190:193], v[18:21]
	v_mfma_f32_16x16x32_bf16 v[58:61], v[156:159], v[198:201], v[58:61]
	v_mfma_f32_16x16x32_bf16 v[22:25], v[164:167], v[198:201], v[22:25]
	v_mfma_f32_16x16x32_bf16 v[54:57], v[156:159], v[206:209], v[54:57]
	v_mfma_f32_16x16x32_bf16 v[26:29], v[164:167], v[206:209], v[26:29]
	v_mfma_f32_16x16x32_bf16 v[50:53], v[156:159], v[214:217], v[50:53]
	v_mfma_f32_16x16x32_bf16 v[30:33], v[164:167], v[214:217], v[30:33]
	v_mfma_f32_16x16x32_bf16 v[46:49], v[168:171], v[186:189], v[46:49]
	v_mfma_f32_16x16x32_bf16 v[2:5], v[176:179], v[186:189], v[2:5]
	v_mfma_f32_16x16x32_bf16 v[42:45], v[168:171], v[194:197], v[42:45]
	v_mfma_f32_16x16x32_bf16 v[6:9], v[176:179], v[194:197], v[6:9]
	v_mfma_f32_16x16x32_bf16 v[38:41], v[168:171], v[202:205], v[38:41]
	v_mfma_f32_16x16x32_bf16 v[10:13], v[176:179], v[202:205], v[10:13]
	v_mfma_f32_16x16x32_bf16 v[34:37], v[168:171], v[210:213], v[34:37]
	v_mfma_f32_16x16x32_bf16 v[14:17], v[176:179], v[210:213], v[14:17]
	v_mfma_f32_16x16x32_bf16 v[46:49], v[172:175], v[190:193], v[46:49]
	v_mfma_f32_16x16x32_bf16 v[2:5], v[182:185], v[190:193], v[2:5]
	v_mfma_f32_16x16x32_bf16 v[42:45], v[172:175], v[198:201], v[42:45]
	v_mfma_f32_16x16x32_bf16 v[6:9], v[182:185], v[198:201], v[6:9]
	v_mfma_f32_16x16x32_bf16 v[38:41], v[172:175], v[206:209], v[38:41]
	v_mfma_f32_16x16x32_bf16 v[10:13], v[182:185], v[206:209], v[10:13]
	v_mfma_f32_16x16x32_bf16 v[34:37], v[172:175], v[214:217], v[34:37]
	v_mfma_f32_16x16x32_bf16 v[14:17], v[182:185], v[214:217], v[14:17]
	s_setprio 0
	s_barrier
	s_add_i32 s56, s56, 2
	s_add_u32 s6, s6, 0x100
	s_addc_u32 s7, s7, 0
	s_cmp_gt_u32 s56, 13
	s_cbranch_scc1 .LBB0_771
